# sc8 + code placement: every K-loop MFMA block padded (s_nop 0 in the preceding load stage) to start on an 8-byte boundary
# baseline (speedup 1.0000x reference)
.LBB0_256:
	s_nop 0
	v_add_u32_e32 v172, s70, v160
	v_add_u32_e32 v188, s71, v160
	ds_read_b128 v[154:157], v172
	ds_read_b128 v[164:167], v172 offset:1024
	ds_read_b128 v[168:171], v172 offset:2048
	ds_read_b128 v[172:175], v172 offset:3072
	ds_read_b128 v[176:179], v188
	ds_read_b128 v[180:183], v188 offset:1024
	ds_read_b128 v[184:187], v188 offset:2048
	ds_read_b128 v[188:191], v188 offset:3072
	s_add_i32 s75, s30, 2
	s_add_u32 s31, s28, 0xfffc0080
	s_addc_u32 s34, s29, -1
	s_cmp_eq_u32 s67, s30
	s_cselect_b32 s30, s26, s17
	s_cselect_b32 s35, s25, s34
	s_cselect_b32 s34, s24, s31
	s_cselect_b32 s31, s27, s19
	s_add_i32 m0, s58, 0xc000
	ds_read_b128 v[192:195], v163
	ds_read_b128 v[196:199], v163 offset:1024
	ds_read_b128 v[200:203], v163 offset:2048
	ds_read_b128 v[204:207], v163 offset:3072
	ds_read_b128 v[208:211], v163 offset:4096
	ds_read_b128 v[212:215], v163 offset:5120
	ds_read_b128 v[216:219], v163 offset:6144
	ds_read_b128 v[220:223], v163 offset:7168
	global_load_lds_dwordx4 v146, s[28:29]
	s_add_i32 m0, s58, 0xe000
	s_nop 0
	global_load_lds_dwordx4 v148, s[28:29]
	s_waitcnt vmcnt(8)
	s_waitcnt lgkmcnt(0)
	s_barrier
	v_mfma_f32_16x16x32_bf16 v[42:45], v[154:157], v[192:195], v[42:45]
	v_mfma_f32_16x16x32_bf16 v[42:45], v[164:167], v[196:199], v[42:45]
	v_mfma_f32_16x16x32_bf16 v[54:57], v[164:167], v[204:207], v[54:57]
	v_mfma_f32_16x16x32_bf16 v[54:57], v[154:157], v[200:203], v[54:57]
	v_mfma_f32_16x16x32_bf16 v[66:69], v[154:157], v[208:211], v[66:69]
	v_mfma_f32_16x16x32_bf16 v[66:69], v[164:167], v[212:215], v[66:69]
	v_mfma_f32_16x16x32_bf16 v[62:65], v[164:167], v[220:223], v[62:65]
	v_mfma_f32_16x16x32_bf16 v[62:65], v[154:157], v[216:219], v[62:65]
	v_mfma_f32_16x16x32_bf16 v[46:49], v[168:171], v[216:219], v[46:49]
	v_mfma_f32_16x16x32_bf16 v[46:49], v[172:175], v[220:223], v[46:49]
	v_mfma_f32_16x16x32_bf16 v[50:53], v[172:175], v[212:215], v[50:53]
	v_mfma_f32_16x16x32_bf16 v[50:53], v[168:171], v[208:211], v[50:53]
	v_mfma_f32_16x16x32_bf16 v[38:41], v[168:171], v[200:203], v[38:41]
	v_mfma_f32_16x16x32_bf16 v[38:41], v[172:175], v[204:207], v[38:41]
	v_mfma_f32_16x16x32_bf16 v[26:29], v[172:175], v[196:199], v[26:29]
	v_mfma_f32_16x16x32_bf16 v[26:29], v[168:171], v[192:195], v[26:29]
	v_mfma_f32_16x16x32_bf16 v[14:17], v[176:179], v[192:195], v[14:17]
	v_mfma_f32_16x16x32_bf16 v[14:17], v[180:183], v[196:199], v[14:17]
	v_mfma_f32_16x16x32_bf16 v[22:25], v[180:183], v[204:207], v[22:25]
	v_mfma_f32_16x16x32_bf16 v[22:25], v[176:179], v[200:203], v[22:25]
	v_mfma_f32_16x16x32_bf16 v[30:33], v[176:179], v[208:211], v[30:33]
	v_mfma_f32_16x16x32_bf16 v[30:33], v[180:183], v[212:215], v[30:33]
	v_mfma_f32_16x16x32_bf16 v[34:37], v[180:183], v[220:223], v[34:37]
	v_mfma_f32_16x16x32_bf16 v[34:37], v[176:179], v[216:219], v[34:37]
	v_mfma_f32_16x16x32_bf16 v[18:21], v[184:187], v[216:219], v[18:21]
	v_mfma_f32_16x16x32_bf16 v[18:21], v[188:191], v[220:223], v[18:21]
	v_mfma_f32_16x16x32_bf16 v[10:13], v[188:191], v[212:215], v[10:13]
	v_mfma_f32_16x16x32_bf16 v[10:13], v[184:187], v[208:211], v[10:13]
	v_mfma_f32_16x16x32_bf16 v[6:9], v[184:187], v[200:203], v[6:9]
	v_mfma_f32_16x16x32_bf16 v[6:9], v[188:191], v[204:207], v[6:9]
	v_mfma_f32_16x16x32_bf16 v[2:5], v[188:191], v[196:199], v[2:5]
	v_mfma_f32_16x16x32_bf16 v[2:5], v[184:187], v[192:195], v[2:5]
	s_barrier
	s_add_i32 s50, s70, s54
	s_mov_b32 m0, s50
	ds_read_b128 v[192:195], v163 offset:16384
	ds_read_b128 v[196:199], v163 offset:17408
	ds_read_b128 v[200:203], v163 offset:18432
	ds_read_b128 v[204:207], v163 offset:19456
	ds_read_b128 v[208:211], v163 offset:20480
	ds_read_b128 v[212:215], v163 offset:21504
	ds_read_b128 v[216:219], v163 offset:22528
	ds_read_b128 v[220:223], v163 offset:23552
	global_load_lds_dwordx4 v134, s[30:31]
	s_add_i32 m0, s50, 0x2000
	s_add_u32 s76, s30, 0x40000
	v_lshl_add_u64 v[226:227], s[30:31], 0, v[130:131]
	s_addc_u32 s77, s31, 0
	s_add_i32 s50, s71, s54
	global_load_lds_dwordx4 v130, s[30:31]
	s_mov_b32 m0, s50
	v_lshl_add_u64 v[230:231], s[34:35], 0, v[132:133]
	global_load_lds_dwordx4 v134, s[76:77]
	s_add_i32 m0, s50, 0x2000
	s_nop 0
	global_load_lds_dwordx4 v130, s[76:77]
	v_lshl_add_u64 v[228:229], s[34:35], 0, v[136:137]
	s_mov_b32 m0, s58
	s_nop 0
	global_load_lds_dwordx4 v136, s[34:35]
	s_mov_b32 m0, s59
	s_nop 0
	global_load_lds_dwordx4 v132, s[34:35]
	s_waitcnt vmcnt(8)
	s_waitcnt lgkmcnt(0)
	s_barrier
	v_mfma_f32_16x16x32_bf16 v[110:113], v[154:157], v[192:195], v[110:113]
	v_mfma_f32_16x16x32_bf16 v[110:113], v[164:167], v[196:199], v[110:113]
	v_mfma_f32_16x16x32_bf16 v[106:109], v[164:167], v[204:207], v[106:109]
	v_mfma_f32_16x16x32_bf16 v[106:109], v[154:157], v[200:203], v[106:109]
	v_mfma_f32_16x16x32_bf16 v[118:121], v[154:157], v[208:211], v[118:121]
	v_mfma_f32_16x16x32_bf16 v[118:121], v[164:167], v[212:215], v[118:121]
	v_mfma_f32_16x16x32_bf16 v[126:129], v[164:167], v[220:223], v[126:129]
	v_mfma_f32_16x16x32_bf16 v[126:129], v[154:157], v[216:219], v[126:129]
	v_mfma_f32_16x16x32_bf16 v[102:105], v[168:171], v[216:219], v[102:105]
	v_mfma_f32_16x16x32_bf16 v[102:105], v[172:175], v[220:223], v[102:105]
	v_mfma_f32_16x16x32_bf16 v[94:97], v[172:175], v[212:215], v[94:97]
	v_mfma_f32_16x16x32_bf16 v[94:97], v[168:171], v[208:211], v[94:97]
	v_mfma_f32_16x16x32_bf16 v[82:85], v[168:171], v[200:203], v[82:85]
	v_mfma_f32_16x16x32_bf16 v[82:85], v[172:175], v[204:207], v[82:85]
	v_mfma_f32_16x16x32_bf16 v[86:89], v[172:175], v[196:199], v[86:89]
	v_mfma_f32_16x16x32_bf16 v[86:89], v[168:171], v[192:195], v[86:89]
	v_mfma_f32_16x16x32_bf16 v[70:73], v[176:179], v[192:195], v[70:73]
	v_mfma_f32_16x16x32_bf16 v[70:73], v[180:183], v[196:199], v[70:73]
	v_mfma_f32_16x16x32_bf16 v[74:77], v[180:183], v[204:207], v[74:77]
	v_mfma_f32_16x16x32_bf16 v[74:77], v[176:179], v[200:203], v[74:77]
	v_mfma_f32_16x16x32_bf16 v[114:117], v[176:179], v[208:211], v[114:117]
	v_mfma_f32_16x16x32_bf16 v[114:117], v[180:183], v[212:215], v[114:117]
	v_mfma_f32_16x16x32_bf16 v[122:125], v[180:183], v[220:223], v[122:125]
	v_mfma_f32_16x16x32_bf16 v[122:125], v[176:179], v[216:219], v[122:125]
	v_mfma_f32_16x16x32_bf16 v[98:101], v[184:187], v[216:219], v[98:101]
	v_mfma_f32_16x16x32_bf16 v[98:101], v[188:191], v[220:223], v[98:101]
	v_mfma_f32_16x16x32_bf16 v[90:93], v[188:191], v[212:215], v[90:93]
	v_mfma_f32_16x16x32_bf16 v[90:93], v[184:187], v[208:211], v[90:93]
	v_mfma_f32_16x16x32_bf16 v[78:81], v[184:187], v[200:203], v[78:81]
	v_mfma_f32_16x16x32_bf16 v[78:81], v[188:191], v[204:207], v[78:81]
	v_mfma_f32_16x16x32_bf16 v[58:61], v[188:191], v[196:199], v[58:61]
	v_mfma_f32_16x16x32_bf16 v[58:61], v[184:187], v[192:195], v[58:61]
	s_barrier
	s_add_i32 s50, 0, 0x18000
	s_add_i32 s51, 0, 0x1c000
	v_add_u32_e32 v172, s50, v160
	v_add_u32_e32 v188, s51, v160
	ds_read_b128 v[154:157], v172
	ds_read_b128 v[164:167], v172 offset:1024
	ds_read_b128 v[168:171], v172 offset:2048
	ds_read_b128 v[172:175], v172 offset:3072
	ds_read_b128 v[176:179], v188
	ds_read_b128 v[180:183], v188 offset:1024
	ds_read_b128 v[184:187], v188 offset:2048
	ds_read_b128 v[188:191], v188 offset:3072
	s_add_u32 s34, s34, 0x40000
	s_addc_u32 s35, s35, 0
	s_mov_b32 m0, s60
	ds_read_b128 v[192:195], v163 offset:32768
	ds_read_b128 v[196:199], v163 offset:33792
	ds_read_b128 v[200:203], v163 offset:34816
	ds_read_b128 v[204:207], v163 offset:35840
	ds_read_b128 v[208:211], v163 offset:36864
	ds_read_b128 v[212:215], v163 offset:37888
	ds_read_b128 v[216:219], v163 offset:38912
	ds_read_b128 v[220:223], v163 offset:39936
	global_load_lds_dwordx4 v136, s[34:35]
	s_mov_b32 m0, s61
	s_nop 0
	global_load_lds_dwordx4 v132, s[34:35]
	s_waitcnt vmcnt(8)
	s_waitcnt lgkmcnt(0)
	s_barrier
	v_mfma_f32_16x16x32_bf16 v[42:45], v[154:157], v[192:195], v[42:45]
	v_mfma_f32_16x16x32_bf16 v[42:45], v[164:167], v[196:199], v[42:45]
	v_mfma_f32_16x16x32_bf16 v[54:57], v[164:167], v[204:207], v[54:57]
	v_mfma_f32_16x16x32_bf16 v[54:57], v[154:157], v[200:203], v[54:57]
	v_mfma_f32_16x16x32_bf16 v[66:69], v[154:157], v[208:211], v[66:69]
	v_mfma_f32_16x16x32_bf16 v[66:69], v[164:167], v[212:215], v[66:69]
	v_mfma_f32_16x16x32_bf16 v[62:65], v[164:167], v[220:223], v[62:65]
	v_mfma_f32_16x16x32_bf16 v[62:65], v[154:157], v[216:219], v[62:65]
	v_mfma_f32_16x16x32_bf16 v[46:49], v[168:171], v[216:219], v[46:49]
	v_mfma_f32_16x16x32_bf16 v[46:49], v[172:175], v[220:223], v[46:49]
	v_mfma_f32_16x16x32_bf16 v[50:53], v[172:175], v[212:215], v[50:53]
	v_mfma_f32_16x16x32_bf16 v[50:53], v[168:171], v[208:211], v[50:53]
	v_mfma_f32_16x16x32_bf16 v[38:41], v[168:171], v[200:203], v[38:41]
	v_mfma_f32_16x16x32_bf16 v[38:41], v[172:175], v[204:207], v[38:41]
	v_mfma_f32_16x16x32_bf16 v[26:29], v[172:175], v[196:199], v[26:29]
	v_mfma_f32_16x16x32_bf16 v[26:29], v[168:171], v[192:195], v[26:29]
	v_mfma_f32_16x16x32_bf16 v[14:17], v[176:179], v[192:195], v[14:17]
	v_mfma_f32_16x16x32_bf16 v[14:17], v[180:183], v[196:199], v[14:17]
	v_mfma_f32_16x16x32_bf16 v[22:25], v[180:183], v[204:207], v[22:25]
	v_mfma_f32_16x16x32_bf16 v[22:25], v[176:179], v[200:203], v[22:25]
	v_mfma_f32_16x16x32_bf16 v[30:33], v[176:179], v[208:211], v[30:33]
	v_mfma_f32_16x16x32_bf16 v[30:33], v[180:183], v[212:215], v[30:33]
	v_mfma_f32_16x16x32_bf16 v[34:37], v[180:183], v[220:223], v[34:37]
	v_mfma_f32_16x16x32_bf16 v[34:37], v[176:179], v[216:219], v[34:37]
	v_mfma_f32_16x16x32_bf16 v[18:21], v[184:187], v[216:219], v[18:21]
	v_mfma_f32_16x16x32_bf16 v[18:21], v[188:191], v[220:223], v[18:21]
	v_mfma_f32_16x16x32_bf16 v[10:13], v[188:191], v[212:215], v[10:13]
	v_mfma_f32_16x16x32_bf16 v[10:13], v[184:187], v[208:211], v[10:13]
	v_mfma_f32_16x16x32_bf16 v[6:9], v[184:187], v[200:203], v[6:9]
	v_mfma_f32_16x16x32_bf16 v[6:9], v[188:191], v[204:207], v[6:9]
	v_mfma_f32_16x16x32_bf16 v[2:5], v[188:191], v[196:199], v[2:5]
	v_mfma_f32_16x16x32_bf16 v[2:5], v[184:187], v[192:195], v[2:5]
	s_barrier
	s_nop 0
	s_add_i32 s34, s50, s54
	s_mov_b32 m0, s34
	ds_read_b128 v[192:195], v163 offset:49152
	ds_read_b128 v[196:199], v163 offset:50176
	ds_read_b128 v[200:203], v163 offset:51200
	ds_read_b128 v[204:207], v163 offset:52224
	ds_read_b128 v[208:211], v163 offset:53248
	ds_read_b128 v[212:215], v163 offset:54272
	ds_read_b128 v[216:219], v163 offset:55296
	ds_read_b128 v[220:223], v163 offset:56320
	s_add_u32 s98, s30, s10
	s_addc_u32 s99, s31, s11
	global_load_lds_dwordx4 v134, s[98:99]
	s_add_i32 m0, s34, 0x2000
	s_add_u32 s30, s30, 0x40080
	v_lshl_add_u64 v[224:225], v[226:227], 0, s[10:11]
	s_addc_u32 s31, s31, 0
	s_add_i32 s34, s51, s54
	global_load_lds_dwordx4 v[224:225], off
	s_mov_b32 m0, s34
	s_nop 0
	global_load_lds_dwordx4 v134, s[30:31]
	s_add_i32 m0, s34, 0x2000
	s_nop 0
	global_load_lds_dwordx4 v130, s[30:31]
	v_lshl_add_u64 v[224:225], v[228:229], 0, s[10:11]
	s_mov_b32 m0, s65
	s_nop 0
	global_load_lds_dwordx4 v[224:225], off
	v_lshl_add_u64 v[224:225], v[230:231], 0, s[10:11]
	s_mov_b32 m0, s66
	s_nop 0
	global_load_lds_dwordx4 v[224:225], off
	s_waitcnt vmcnt(8)
	s_waitcnt lgkmcnt(0)
	s_barrier
	v_mfma_f32_16x16x32_bf16 v[110:113], v[154:157], v[192:195], v[110:113]
	v_mfma_f32_16x16x32_bf16 v[110:113], v[164:167], v[196:199], v[110:113]
	v_mfma_f32_16x16x32_bf16 v[106:109], v[164:167], v[204:207], v[106:109]
	v_mfma_f32_16x16x32_bf16 v[106:109], v[154:157], v[200:203], v[106:109]
	v_mfma_f32_16x16x32_bf16 v[118:121], v[154:157], v[208:211], v[118:121]
	v_mfma_f32_16x16x32_bf16 v[118:121], v[164:167], v[212:215], v[118:121]
	v_mfma_f32_16x16x32_bf16 v[126:129], v[164:167], v[220:223], v[126:129]
	v_mfma_f32_16x16x32_bf16 v[126:129], v[154:157], v[216:219], v[126:129]
	v_mfma_f32_16x16x32_bf16 v[102:105], v[168:171], v[216:219], v[102:105]
	v_mfma_f32_16x16x32_bf16 v[102:105], v[172:175], v[220:223], v[102:105]
	v_mfma_f32_16x16x32_bf16 v[94:97], v[172:175], v[212:215], v[94:97]
	v_mfma_f32_16x16x32_bf16 v[94:97], v[168:171], v[208:211], v[94:97]
	v_mfma_f32_16x16x32_bf16 v[82:85], v[168:171], v[200:203], v[82:85]
	v_mfma_f32_16x16x32_bf16 v[82:85], v[172:175], v[204:207], v[82:85]
	v_mfma_f32_16x16x32_bf16 v[86:89], v[172:175], v[196:199], v[86:89]
	v_mfma_f32_16x16x32_bf16 v[86:89], v[168:171], v[192:195], v[86:89]
	v_mfma_f32_16x16x32_bf16 v[70:73], v[176:179], v[192:195], v[70:73]
	v_mfma_f32_16x16x32_bf16 v[70:73], v[180:183], v[196:199], v[70:73]
	v_mfma_f32_16x16x32_bf16 v[74:77], v[180:183], v[204:207], v[74:77]
	v_mfma_f32_16x16x32_bf16 v[74:77], v[176:179], v[200:203], v[74:77]
	v_mfma_f32_16x16x32_bf16 v[114:117], v[176:179], v[208:211], v[114:117]
	v_mfma_f32_16x16x32_bf16 v[114:117], v[180:183], v[212:215], v[114:117]
	v_mfma_f32_16x16x32_bf16 v[122:125], v[180:183], v[220:223], v[122:125]
	v_mfma_f32_16x16x32_bf16 v[122:125], v[176:179], v[216:219], v[122:125]
	v_mfma_f32_16x16x32_bf16 v[98:101], v[184:187], v[216:219], v[98:101]
	v_mfma_f32_16x16x32_bf16 v[98:101], v[188:191], v[220:223], v[98:101]
	v_mfma_f32_16x16x32_bf16 v[90:93], v[188:191], v[212:215], v[90:93]
	v_mfma_f32_16x16x32_bf16 v[90:93], v[184:187], v[208:211], v[90:93]
	v_mfma_f32_16x16x32_bf16 v[78:81], v[184:187], v[200:203], v[78:81]
	v_mfma_f32_16x16x32_bf16 v[78:81], v[188:191], v[204:207], v[78:81]
	v_mfma_f32_16x16x32_bf16 v[58:61], v[188:191], v[196:199], v[58:61]
	v_mfma_f32_16x16x32_bf16 v[58:61], v[184:187], v[192:195], v[58:61]
	s_barrier
	s_add_u32 s28, s28, 0x100
	s_addc_u32 s29, s29, 0
	s_add_u32 s17, s17, 0x100
	s_addc_u32 s19, s19, 0
	s_cmp_ge_i32 s75, s62
	s_mov_b32 s30, s75
	s_cbranch_scc0 .LBB0_256

.LBB0_351:
	s_nop 0
	v_add_u32_e32 v81, s62, v78
	s_waitcnt lgkmcnt(0)
	ds_read_b128 v[82:85], v81
	ds_read_b128 v[86:89], v81 offset:1024
	ds_read_b128 v[90:93], v81 offset:2048
	ds_read_b128 v[94:97], v81 offset:3072
	s_add_i32 s72, s24, 2
	s_add_u32 s22, s20, 0x100
	s_addc_u32 s23, s21, 0
	s_cmp_eq_u32 s61, s24
	s_cselect_b32 s24, s16, s70
	s_cselect_b32 s27, s15, s23
	s_cselect_b32 s26, s14, s22
	s_cselect_b32 s25, s17, s71
	s_mov_b32 m0, s63
	ds_read_b128 v[98:101], v79
	ds_read_b128 v[102:105], v79 offset:1024
	ds_read_b128 v[106:109], v79 offset:2048
	ds_read_b128 v[110:113], v79 offset:3072
	ds_read_b128 v[114:117], v79 offset:4096
	ds_read_b128 v[118:121], v79 offset:5120
	ds_read_b128 v[122:125], v79 offset:6144
	ds_read_b128 v[126:129], v79 offset:7168
	global_load_lds_dwordx4 v74, s[20:21]
	s_mov_b32 m0, s64
	s_nop 0
	global_load_lds_dwordx4 v76, s[20:21]
	s_waitcnt vmcnt(8)
	s_waitcnt lgkmcnt(0)
	s_barrier
	v_mfma_f32_16x16x32_bf16 v[62:65], v[82:85], v[98:101], v[62:65]
	v_mfma_f32_16x16x32_bf16 v[62:65], v[86:89], v[102:105], v[62:65]
	v_mfma_f32_16x16x32_bf16 v[54:57], v[86:89], v[110:113], v[54:57]
	v_mfma_f32_16x16x32_bf16 v[54:57], v[82:85], v[106:109], v[54:57]
	v_mfma_f32_16x16x32_bf16 v[46:49], v[82:85], v[114:117], v[46:49]
	v_mfma_f32_16x16x32_bf16 v[46:49], v[86:89], v[118:121], v[46:49]
	v_mfma_f32_16x16x32_bf16 v[34:37], v[86:89], v[126:129], v[34:37]
	v_mfma_f32_16x16x32_bf16 v[34:37], v[82:85], v[122:125], v[34:37]
	v_mfma_f32_16x16x32_bf16 v[26:29], v[90:93], v[122:125], v[26:29]
	v_mfma_f32_16x16x32_bf16 v[26:29], v[94:97], v[126:129], v[26:29]
	v_mfma_f32_16x16x32_bf16 v[42:45], v[94:97], v[118:121], v[42:45]
	v_mfma_f32_16x16x32_bf16 v[42:45], v[90:93], v[114:117], v[42:45]
	v_mfma_f32_16x16x32_bf16 v[50:53], v[90:93], v[106:109], v[50:53]
	v_mfma_f32_16x16x32_bf16 v[50:53], v[94:97], v[110:113], v[50:53]
	v_mfma_f32_16x16x32_bf16 v[58:61], v[94:97], v[102:105], v[58:61]
	v_mfma_f32_16x16x32_bf16 v[58:61], v[90:93], v[98:101], v[58:61]
	s_barrier
	s_mov_b32 m0, s65
	s_add_u32 s20, s24, 0x10000
	ds_read_b128 v[98:101], v79 offset:16384
	ds_read_b128 v[102:105], v79 offset:17408
	ds_read_b128 v[106:109], v79 offset:18432
	ds_read_b128 v[110:113], v79 offset:19456
	ds_read_b128 v[114:117], v79 offset:20480
	ds_read_b128 v[118:121], v79 offset:21504
	ds_read_b128 v[122:125], v79 offset:22528
	ds_read_b128 v[126:129], v79 offset:23552
	global_load_lds_dwordx4 v70, s[24:25]
	s_mov_b32 m0, s66
	s_addc_u32 s21, s25, 0
	global_load_lds_dwordx4 v66, s[24:25]
	s_mov_b32 m0, s34
	global_load_lds_dwordx4 v70, s[20:21]
	s_mov_b32 m0, s35
	s_nop 0
	global_load_lds_dwordx4 v66, s[20:21]
	s_mov_b32 m0, s31
	s_nop 0
	global_load_lds_dwordx4 v72, s[26:27]
	s_mov_b32 m0, s52
	s_nop 0
	global_load_lds_dwordx4 v68, s[26:27]
	s_waitcnt vmcnt(8)
	s_waitcnt lgkmcnt(0)
	s_barrier
	v_mfma_f32_16x16x32_bf16 v[38:41], v[82:85], v[98:101], v[38:41]
	v_mfma_f32_16x16x32_bf16 v[38:41], v[86:89], v[102:105], v[38:41]
	v_mfma_f32_16x16x32_bf16 v[22:25], v[86:89], v[110:113], v[22:25]
	v_mfma_f32_16x16x32_bf16 v[22:25], v[82:85], v[106:109], v[22:25]
	v_mfma_f32_16x16x32_bf16 v[14:17], v[82:85], v[114:117], v[14:17]
	v_mfma_f32_16x16x32_bf16 v[14:17], v[86:89], v[118:121], v[14:17]
	v_mfma_f32_16x16x32_bf16 v[6:9], v[86:89], v[126:129], v[6:9]
	v_mfma_f32_16x16x32_bf16 v[6:9], v[82:85], v[122:125], v[6:9]
	v_mfma_f32_16x16x32_bf16 v[2:5], v[90:93], v[122:125], v[2:5]
	v_mfma_f32_16x16x32_bf16 v[2:5], v[94:97], v[126:129], v[2:5]
	v_mfma_f32_16x16x32_bf16 v[10:13], v[94:97], v[118:121], v[10:13]
	v_mfma_f32_16x16x32_bf16 v[10:13], v[90:93], v[114:117], v[10:13]
	v_mfma_f32_16x16x32_bf16 v[18:21], v[90:93], v[106:109], v[18:21]
	v_mfma_f32_16x16x32_bf16 v[18:21], v[94:97], v[110:113], v[18:21]
	v_mfma_f32_16x16x32_bf16 v[30:33], v[94:97], v[102:105], v[30:33]
	v_mfma_f32_16x16x32_bf16 v[30:33], v[90:93], v[98:101], v[30:33]
	s_barrier
	s_nop 0
	v_add_u32_e32 v81, s67, v78
	ds_read_b128 v[82:85], v81
	ds_read_b128 v[86:89], v81 offset:1024
	ds_read_b128 v[90:93], v81 offset:2048
	ds_read_b128 v[94:97], v81 offset:3072
	s_add_u32 s20, s26, 0x18000
	s_addc_u32 s21, s27, 0
	s_mov_b32 m0, s53
	ds_read_b128 v[98:101], v79 offset:32768
	ds_read_b128 v[102:105], v79 offset:33792
	ds_read_b128 v[106:109], v79 offset:34816
	ds_read_b128 v[110:113], v79 offset:35840
	ds_read_b128 v[114:117], v79 offset:36864
	ds_read_b128 v[118:121], v79 offset:37888
	ds_read_b128 v[122:125], v79 offset:38912
	ds_read_b128 v[126:129], v79 offset:39936
	global_load_lds_dwordx4 v72, s[20:21]
	s_mov_b32 m0, s54
	s_nop 0
	global_load_lds_dwordx4 v68, s[20:21]
	s_waitcnt vmcnt(8)
	s_waitcnt lgkmcnt(0)
	s_barrier
	v_mfma_f32_16x16x32_bf16 v[62:65], v[82:85], v[98:101], v[62:65]
	v_mfma_f32_16x16x32_bf16 v[62:65], v[86:89], v[102:105], v[62:65]
	v_mfma_f32_16x16x32_bf16 v[54:57], v[86:89], v[110:113], v[54:57]
	v_mfma_f32_16x16x32_bf16 v[54:57], v[82:85], v[106:109], v[54:57]
	v_mfma_f32_16x16x32_bf16 v[46:49], v[82:85], v[114:117], v[46:49]
	v_mfma_f32_16x16x32_bf16 v[46:49], v[86:89], v[118:121], v[46:49]
	v_mfma_f32_16x16x32_bf16 v[34:37], v[86:89], v[126:129], v[34:37]
	v_mfma_f32_16x16x32_bf16 v[34:37], v[82:85], v[122:125], v[34:37]
	v_mfma_f32_16x16x32_bf16 v[26:29], v[90:93], v[122:125], v[26:29]
	v_mfma_f32_16x16x32_bf16 v[26:29], v[94:97], v[126:129], v[26:29]
	v_mfma_f32_16x16x32_bf16 v[42:45], v[94:97], v[118:121], v[42:45]
	v_mfma_f32_16x16x32_bf16 v[42:45], v[90:93], v[114:117], v[42:45]
	v_mfma_f32_16x16x32_bf16 v[50:53], v[90:93], v[106:109], v[50:53]
	v_mfma_f32_16x16x32_bf16 v[50:53], v[94:97], v[110:113], v[50:53]
	v_mfma_f32_16x16x32_bf16 v[58:61], v[94:97], v[102:105], v[58:61]
	v_mfma_f32_16x16x32_bf16 v[58:61], v[90:93], v[98:101], v[58:61]
	s_barrier
	s_nop 0
	s_mov_b32 m0, s68
	s_add_u32 s20, s24, 0x10080
	ds_read_b128 v[98:101], v79 offset:49152
	ds_read_b128 v[102:105], v79 offset:50176
	ds_read_b128 v[106:109], v79 offset:51200
	ds_read_b128 v[110:113], v79 offset:52224
	ds_read_b128 v[114:117], v79 offset:53248
	ds_read_b128 v[118:121], v79 offset:54272
	ds_read_b128 v[122:125], v79 offset:55296
	ds_read_b128 v[126:129], v79 offset:56320
	s_add_u32 s98, s24, s6
	s_addc_u32 s99, s25, s7
	global_load_lds_dwordx4 v70, s[98:99]
	s_mov_b32 m0, s69
	s_addc_u32 s21, s25, 0
	s_add_u32 s100, s24, s6
	s_addc_u32 s101, s25, s7
	global_load_lds_dwordx4 v66, s[100:101]
	s_mov_b32 m0, s59
	s_nop 0
	global_load_lds_dwordx4 v70, s[20:21]
	s_mov_b32 m0, s60
	s_nop 0
	global_load_lds_dwordx4 v66, s[20:21]
	s_mov_b32 m0, s57
	s_nop 0
	s_add_u32 s98, s26, s6
	s_addc_u32 s99, s27, s7
	global_load_lds_dwordx4 v72, s[98:99]
	s_mov_b32 m0, s58
	s_nop 0
	s_add_u32 s100, s26, s6
	s_addc_u32 s101, s27, s7
	global_load_lds_dwordx4 v68, s[100:101]
	s_waitcnt vmcnt(8)
	s_waitcnt lgkmcnt(0)
	s_barrier
	v_mfma_f32_16x16x32_bf16 v[38:41], v[82:85], v[98:101], v[38:41]
	v_mfma_f32_16x16x32_bf16 v[38:41], v[86:89], v[102:105], v[38:41]
	v_mfma_f32_16x16x32_bf16 v[22:25], v[86:89], v[110:113], v[22:25]
	v_mfma_f32_16x16x32_bf16 v[22:25], v[82:85], v[106:109], v[22:25]
	v_mfma_f32_16x16x32_bf16 v[14:17], v[82:85], v[114:117], v[14:17]
	v_mfma_f32_16x16x32_bf16 v[14:17], v[86:89], v[118:121], v[14:17]
	v_mfma_f32_16x16x32_bf16 v[6:9], v[86:89], v[126:129], v[6:9]
	v_mfma_f32_16x16x32_bf16 v[6:9], v[82:85], v[122:125], v[6:9]
	v_mfma_f32_16x16x32_bf16 v[2:5], v[90:93], v[122:125], v[2:5]
	v_mfma_f32_16x16x32_bf16 v[2:5], v[94:97], v[126:129], v[2:5]
	v_mfma_f32_16x16x32_bf16 v[10:13], v[94:97], v[118:121], v[10:13]
	v_mfma_f32_16x16x32_bf16 v[10:13], v[90:93], v[114:117], v[10:13]
	v_mfma_f32_16x16x32_bf16 v[18:21], v[90:93], v[106:109], v[18:21]
	v_mfma_f32_16x16x32_bf16 v[18:21], v[94:97], v[110:113], v[18:21]
	v_mfma_f32_16x16x32_bf16 v[30:33], v[94:97], v[102:105], v[30:33]
	v_mfma_f32_16x16x32_bf16 v[30:33], v[90:93], v[98:101], v[30:33]
	s_barrier
	s_add_u32 s70, s70, 0x100
	s_addc_u32 s71, s71, 0
	s_cmp_ge_i32 s72, s56
	s_mov_b64 s[20:21], s[22:23]
	s_mov_b32 s24, s72
	s_cbranch_scc0 .LBB0_351

.LBB0_468:
	s_nop 0
	v_add_u32_e32 v144, s62, v1
	ds_read_b128 v[150:153], v144
	ds_read_b128 v[154:157], v144 offset:1024
	ds_read_b128 v[158:161], v144 offset:2048
	ds_read_b128 v[162:165], v144 offset:3072
	v_add_u32_e32 v144, s63, v1
	ds_read_b128 v[166:169], v144
	ds_read_b128 v[170:173], v144 offset:1024
	ds_read_b128 v[174:177], v144 offset:2048
	ds_read_b128 v[178:181], v144 offset:3072
	s_add_i32 s77, s26, 2
	s_add_u32 s24, s22, 0x100
	s_addc_u32 s25, s23, 0
	s_cmp_eq_u32 s61, s26
	s_cselect_b32 s26, s16, s75
	s_cselect_b32 s29, s15, s25
	s_cselect_b32 s28, s14, s24
	s_cselect_b32 s27, s17, s76
	s_mov_b32 m0, s64
	ds_read_b128 v[182:185], v149
	ds_read_b128 v[186:189], v149 offset:1024
	ds_read_b128 v[190:193], v149 offset:2048
	ds_read_b128 v[194:197], v149 offset:3072
	ds_read_b128 v[198:201], v149 offset:4096
	ds_read_b128 v[202:205], v149 offset:5120
	ds_read_b128 v[206:209], v149 offset:6144
	ds_read_b128 v[210:213], v149 offset:7168
	global_load_lds_dwordx4 v140, s[22:23]
	s_mov_b32 m0, s65
	s_nop 0
	global_load_lds_dwordx4 v142, s[22:23]
	s_waitcnt vmcnt(8)
	s_waitcnt lgkmcnt(0)
	s_barrier
	v_mfma_f32_16x16x32_bf16 v[126:129], v[150:153], v[182:185], v[126:129]
	v_mfma_f32_16x16x32_bf16 v[126:129], v[154:157], v[186:189], v[126:129]
	v_mfma_f32_16x16x32_bf16 v[110:113], v[154:157], v[194:197], v[110:113]
	v_mfma_f32_16x16x32_bf16 v[110:113], v[150:153], v[190:193], v[110:113]
	v_mfma_f32_16x16x32_bf16 v[94:97], v[150:153], v[198:201], v[94:97]
	v_mfma_f32_16x16x32_bf16 v[94:97], v[154:157], v[202:205], v[94:97]
	v_mfma_f32_16x16x32_bf16 v[78:81], v[154:157], v[210:213], v[78:81]
	v_mfma_f32_16x16x32_bf16 v[78:81], v[150:153], v[206:209], v[78:81]
	v_mfma_f32_16x16x32_bf16 v[74:77], v[158:161], v[206:209], v[74:77]
	v_mfma_f32_16x16x32_bf16 v[74:77], v[162:165], v[210:213], v[74:77]
	v_mfma_f32_16x16x32_bf16 v[90:93], v[162:165], v[202:205], v[90:93]
	v_mfma_f32_16x16x32_bf16 v[90:93], v[158:161], v[198:201], v[90:93]
	v_mfma_f32_16x16x32_bf16 v[106:109], v[158:161], v[190:193], v[106:109]
	v_mfma_f32_16x16x32_bf16 v[106:109], v[162:165], v[194:197], v[106:109]
	v_mfma_f32_16x16x32_bf16 v[122:125], v[162:165], v[186:189], v[122:125]
	v_mfma_f32_16x16x32_bf16 v[122:125], v[158:161], v[182:185], v[122:125]
	v_mfma_f32_16x16x32_bf16 v[118:121], v[166:169], v[182:185], v[118:121]
	v_mfma_f32_16x16x32_bf16 v[118:121], v[170:173], v[186:189], v[118:121]
	v_mfma_f32_16x16x32_bf16 v[102:105], v[170:173], v[194:197], v[102:105]
	v_mfma_f32_16x16x32_bf16 v[102:105], v[166:169], v[190:193], v[102:105]
	v_mfma_f32_16x16x32_bf16 v[86:89], v[166:169], v[198:201], v[86:89]
	v_mfma_f32_16x16x32_bf16 v[86:89], v[170:173], v[202:205], v[86:89]
	v_mfma_f32_16x16x32_bf16 v[70:73], v[170:173], v[210:213], v[70:73]
	v_mfma_f32_16x16x32_bf16 v[70:73], v[166:169], v[206:209], v[70:73]
	v_mfma_f32_16x16x32_bf16 v[66:69], v[174:177], v[206:209], v[66:69]
	v_mfma_f32_16x16x32_bf16 v[66:69], v[178:181], v[210:213], v[66:69]
	v_mfma_f32_16x16x32_bf16 v[82:85], v[178:181], v[202:205], v[82:85]
	v_mfma_f32_16x16x32_bf16 v[82:85], v[174:177], v[198:201], v[82:85]
	v_mfma_f32_16x16x32_bf16 v[98:101], v[174:177], v[190:193], v[98:101]
	v_mfma_f32_16x16x32_bf16 v[98:101], v[178:181], v[194:197], v[98:101]
	v_mfma_f32_16x16x32_bf16 v[114:117], v[178:181], v[186:189], v[114:117]
	v_mfma_f32_16x16x32_bf16 v[114:117], v[174:177], v[182:185], v[114:117]
	s_barrier
	s_mov_b32 m0, s66
	s_add_u32 s22, s26, 0x18000
	ds_read_b128 v[182:185], v149 offset:16384
	ds_read_b128 v[186:189], v149 offset:17408
	ds_read_b128 v[190:193], v149 offset:18432
	ds_read_b128 v[194:197], v149 offset:19456
	ds_read_b128 v[198:201], v149 offset:20480
	ds_read_b128 v[202:205], v149 offset:21504
	ds_read_b128 v[206:209], v149 offset:22528
	ds_read_b128 v[210:213], v149 offset:23552
	global_load_lds_dwordx4 v134, s[26:27]
	v_lshl_add_u64 v[214:215], s[26:27], 0, v[130:131]
	s_mov_b32 m0, s67
	s_addc_u32 s23, s27, 0
	global_load_lds_dwordx4 v130, s[26:27]
	s_mov_b32 m0, s68
	global_load_lds_dwordx4 v134, s[22:23]
	s_mov_b32 m0, s69
	s_nop 0
	global_load_lds_dwordx4 v130, s[22:23]
	s_mov_b32 m0, s34
	s_nop 0
	global_load_lds_dwordx4 v136, s[28:29]
	s_mov_b32 m0, s35
	s_nop 0
	global_load_lds_dwordx4 v132, s[28:29]
	s_waitcnt vmcnt(8)
	s_waitcnt lgkmcnt(0)
	s_barrier
	v_mfma_f32_16x16x32_bf16 v[62:65], v[150:153], v[182:185], v[62:65]
	v_mfma_f32_16x16x32_bf16 v[62:65], v[154:157], v[186:189], v[62:65]
	v_mfma_f32_16x16x32_bf16 v[46:49], v[154:157], v[194:197], v[46:49]
	v_mfma_f32_16x16x32_bf16 v[46:49], v[150:153], v[190:193], v[46:49]
	v_mfma_f32_16x16x32_bf16 v[30:33], v[150:153], v[198:201], v[30:33]
	v_mfma_f32_16x16x32_bf16 v[30:33], v[154:157], v[202:205], v[30:33]
	v_mfma_f32_16x16x32_bf16 v[14:17], v[154:157], v[210:213], v[14:17]
	v_mfma_f32_16x16x32_bf16 v[14:17], v[150:153], v[206:209], v[14:17]
	v_mfma_f32_16x16x32_bf16 v[10:13], v[158:161], v[206:209], v[10:13]
	v_mfma_f32_16x16x32_bf16 v[10:13], v[162:165], v[210:213], v[10:13]
	v_mfma_f32_16x16x32_bf16 v[26:29], v[162:165], v[202:205], v[26:29]
	v_mfma_f32_16x16x32_bf16 v[26:29], v[158:161], v[198:201], v[26:29]
	v_mfma_f32_16x16x32_bf16 v[42:45], v[158:161], v[190:193], v[42:45]
	v_mfma_f32_16x16x32_bf16 v[42:45], v[162:165], v[194:197], v[42:45]
	v_mfma_f32_16x16x32_bf16 v[58:61], v[162:165], v[186:189], v[58:61]
	v_mfma_f32_16x16x32_bf16 v[58:61], v[158:161], v[182:185], v[58:61]
	v_mfma_f32_16x16x32_bf16 v[54:57], v[166:169], v[182:185], v[54:57]
	v_mfma_f32_16x16x32_bf16 v[54:57], v[170:173], v[186:189], v[54:57]
	v_mfma_f32_16x16x32_bf16 v[38:41], v[170:173], v[194:197], v[38:41]
	v_mfma_f32_16x16x32_bf16 v[38:41], v[166:169], v[190:193], v[38:41]
	v_mfma_f32_16x16x32_bf16 v[22:25], v[166:169], v[198:201], v[22:25]
	v_mfma_f32_16x16x32_bf16 v[22:25], v[170:173], v[202:205], v[22:25]
	v_mfma_f32_16x16x32_bf16 v[6:9], v[170:173], v[210:213], v[6:9]
	v_mfma_f32_16x16x32_bf16 v[6:9], v[166:169], v[206:209], v[6:9]
	v_mfma_f32_16x16x32_bf16 v[2:5], v[174:177], v[206:209], v[2:5]
	v_mfma_f32_16x16x32_bf16 v[2:5], v[178:181], v[210:213], v[2:5]
	v_mfma_f32_16x16x32_bf16 v[18:21], v[178:181], v[202:205], v[18:21]
	v_mfma_f32_16x16x32_bf16 v[18:21], v[174:177], v[198:201], v[18:21]
	v_mfma_f32_16x16x32_bf16 v[34:37], v[174:177], v[190:193], v[34:37]
	v_mfma_f32_16x16x32_bf16 v[34:37], v[178:181], v[194:197], v[34:37]
	v_mfma_f32_16x16x32_bf16 v[50:53], v[178:181], v[186:189], v[50:53]
	v_mfma_f32_16x16x32_bf16 v[50:53], v[174:177], v[182:185], v[50:53]
	s_barrier
	v_add_u32_e32 v162, s70, v1
	v_add_u32_e32 v178, s71, v1
	ds_read_b128 v[150:153], v162
	ds_read_b128 v[154:157], v162 offset:1024
	ds_read_b128 v[158:161], v162 offset:2048
	ds_read_b128 v[162:165], v162 offset:3072
	ds_read_b128 v[166:169], v178
	ds_read_b128 v[170:173], v178 offset:1024
	ds_read_b128 v[174:177], v178 offset:2048
	ds_read_b128 v[178:181], v178 offset:3072
	s_add_u32 s22, s28, 0x18000
	s_addc_u32 s23, s29, 0
	s_mov_b32 m0, s52
	ds_read_b128 v[182:185], v149 offset:32768
	ds_read_b128 v[186:189], v149 offset:33792
	ds_read_b128 v[190:193], v149 offset:34816
	ds_read_b128 v[194:197], v149 offset:35840
	ds_read_b128 v[198:201], v149 offset:36864
	ds_read_b128 v[202:205], v149 offset:37888
	ds_read_b128 v[206:209], v149 offset:38912
	ds_read_b128 v[210:213], v149 offset:39936
	global_load_lds_dwordx4 v136, s[22:23]
	s_mov_b32 m0, s53
	s_nop 0
	global_load_lds_dwordx4 v132, s[22:23]
	s_waitcnt vmcnt(8)
	s_waitcnt lgkmcnt(0)
	s_barrier
	v_mfma_f32_16x16x32_bf16 v[126:129], v[150:153], v[182:185], v[126:129]
	v_mfma_f32_16x16x32_bf16 v[126:129], v[154:157], v[186:189], v[126:129]
	v_mfma_f32_16x16x32_bf16 v[110:113], v[154:157], v[194:197], v[110:113]
	v_mfma_f32_16x16x32_bf16 v[110:113], v[150:153], v[190:193], v[110:113]
	v_mfma_f32_16x16x32_bf16 v[94:97], v[150:153], v[198:201], v[94:97]
	v_mfma_f32_16x16x32_bf16 v[94:97], v[154:157], v[202:205], v[94:97]
	v_mfma_f32_16x16x32_bf16 v[78:81], v[154:157], v[210:213], v[78:81]
	v_mfma_f32_16x16x32_bf16 v[78:81], v[150:153], v[206:209], v[78:81]
	v_mfma_f32_16x16x32_bf16 v[74:77], v[158:161], v[206:209], v[74:77]
	v_mfma_f32_16x16x32_bf16 v[74:77], v[162:165], v[210:213], v[74:77]
	v_mfma_f32_16x16x32_bf16 v[90:93], v[162:165], v[202:205], v[90:93]
	v_mfma_f32_16x16x32_bf16 v[90:93], v[158:161], v[198:201], v[90:93]
	v_mfma_f32_16x16x32_bf16 v[106:109], v[158:161], v[190:193], v[106:109]
	v_mfma_f32_16x16x32_bf16 v[106:109], v[162:165], v[194:197], v[106:109]
	v_mfma_f32_16x16x32_bf16 v[122:125], v[162:165], v[186:189], v[122:125]
	v_mfma_f32_16x16x32_bf16 v[122:125], v[158:161], v[182:185], v[122:125]
	v_mfma_f32_16x16x32_bf16 v[118:121], v[166:169], v[182:185], v[118:121]
	v_mfma_f32_16x16x32_bf16 v[118:121], v[170:173], v[186:189], v[118:121]
	v_mfma_f32_16x16x32_bf16 v[102:105], v[170:173], v[194:197], v[102:105]
	v_mfma_f32_16x16x32_bf16 v[102:105], v[166:169], v[190:193], v[102:105]
	v_mfma_f32_16x16x32_bf16 v[86:89], v[166:169], v[198:201], v[86:89]
	v_mfma_f32_16x16x32_bf16 v[86:89], v[170:173], v[202:205], v[86:89]
	v_mfma_f32_16x16x32_bf16 v[70:73], v[170:173], v[210:213], v[70:73]
	v_mfma_f32_16x16x32_bf16 v[70:73], v[166:169], v[206:209], v[70:73]
	v_mfma_f32_16x16x32_bf16 v[66:69], v[174:177], v[206:209], v[66:69]
	v_mfma_f32_16x16x32_bf16 v[66:69], v[178:181], v[210:213], v[66:69]
	v_mfma_f32_16x16x32_bf16 v[82:85], v[178:181], v[202:205], v[82:85]
	v_mfma_f32_16x16x32_bf16 v[82:85], v[174:177], v[198:201], v[82:85]
	v_mfma_f32_16x16x32_bf16 v[98:101], v[174:177], v[190:193], v[98:101]
	v_mfma_f32_16x16x32_bf16 v[98:101], v[178:181], v[194:197], v[98:101]
	v_mfma_f32_16x16x32_bf16 v[114:117], v[178:181], v[186:189], v[114:117]
	v_mfma_f32_16x16x32_bf16 v[114:117], v[174:177], v[182:185], v[114:117]
	s_barrier
	s_mov_b32 m0, s72
	ds_read_b128 v[182:185], v149 offset:49152
	ds_read_b128 v[186:189], v149 offset:50176
	ds_read_b128 v[190:193], v149 offset:51200
	ds_read_b128 v[194:197], v149 offset:52224
	ds_read_b128 v[198:201], v149 offset:53248
	ds_read_b128 v[202:205], v149 offset:54272
	ds_read_b128 v[206:209], v149 offset:55296
	ds_read_b128 v[210:213], v149 offset:56320
	s_add_u32 s98, s26, s4
	s_addc_u32 s99, s27, s5
	global_load_lds_dwordx4 v134, s[98:99]
	s_add_i32 m0, s72, 0x2000
	s_add_u32 s22, s26, 0x18080
	v_lshl_add_u64 v[144:145], v[214:215], 0, s[4:5]
	s_addc_u32 s23, s27, 0
	s_add_i32 s26, s71, s30
	global_load_lds_dwordx4 v[144:145], off
	s_mov_b32 m0, s26
	s_nop 0
	global_load_lds_dwordx4 v134, s[22:23]
	s_add_i32 m0, s26, 0x2000
	s_nop 0
	global_load_lds_dwordx4 v130, s[22:23]
	s_mov_b32 m0, s59
	s_nop 0
	s_add_u32 s100, s28, s4
	s_addc_u32 s101, s29, s5
	global_load_lds_dwordx4 v136, s[100:101]
	s_mov_b32 m0, s60
	s_nop 0
	s_add_u32 s98, s28, s4
	s_addc_u32 s99, s29, s5
	global_load_lds_dwordx4 v132, s[98:99]
	s_waitcnt vmcnt(8)
	s_waitcnt lgkmcnt(0)
	s_barrier
	v_mfma_f32_16x16x32_bf16 v[62:65], v[150:153], v[182:185], v[62:65]
	v_mfma_f32_16x16x32_bf16 v[62:65], v[154:157], v[186:189], v[62:65]
	v_mfma_f32_16x16x32_bf16 v[46:49], v[154:157], v[194:197], v[46:49]
	v_mfma_f32_16x16x32_bf16 v[46:49], v[150:153], v[190:193], v[46:49]
	v_mfma_f32_16x16x32_bf16 v[30:33], v[150:153], v[198:201], v[30:33]
	v_mfma_f32_16x16x32_bf16 v[30:33], v[154:157], v[202:205], v[30:33]
	v_mfma_f32_16x16x32_bf16 v[14:17], v[154:157], v[210:213], v[14:17]
	v_mfma_f32_16x16x32_bf16 v[14:17], v[150:153], v[206:209], v[14:17]
	v_mfma_f32_16x16x32_bf16 v[10:13], v[158:161], v[206:209], v[10:13]
	v_mfma_f32_16x16x32_bf16 v[10:13], v[162:165], v[210:213], v[10:13]
	v_mfma_f32_16x16x32_bf16 v[26:29], v[162:165], v[202:205], v[26:29]
	v_mfma_f32_16x16x32_bf16 v[26:29], v[158:161], v[198:201], v[26:29]
	v_mfma_f32_16x16x32_bf16 v[42:45], v[158:161], v[190:193], v[42:45]
	v_mfma_f32_16x16x32_bf16 v[42:45], v[162:165], v[194:197], v[42:45]
	v_mfma_f32_16x16x32_bf16 v[58:61], v[162:165], v[186:189], v[58:61]
	v_mfma_f32_16x16x32_bf16 v[58:61], v[158:161], v[182:185], v[58:61]
	v_mfma_f32_16x16x32_bf16 v[54:57], v[166:169], v[182:185], v[54:57]
	v_mfma_f32_16x16x32_bf16 v[54:57], v[170:173], v[186:189], v[54:57]
	v_mfma_f32_16x16x32_bf16 v[38:41], v[170:173], v[194:197], v[38:41]
	v_mfma_f32_16x16x32_bf16 v[38:41], v[166:169], v[190:193], v[38:41]
	v_mfma_f32_16x16x32_bf16 v[22:25], v[166:169], v[198:201], v[22:25]
	v_mfma_f32_16x16x32_bf16 v[22:25], v[170:173], v[202:205], v[22:25]
	v_mfma_f32_16x16x32_bf16 v[6:9], v[170:173], v[210:213], v[6:9]
	v_mfma_f32_16x16x32_bf16 v[6:9], v[166:169], v[206:209], v[6:9]
	v_mfma_f32_16x16x32_bf16 v[2:5], v[174:177], v[206:209], v[2:5]
	v_mfma_f32_16x16x32_bf16 v[2:5], v[178:181], v[210:213], v[2:5]
	v_mfma_f32_16x16x32_bf16 v[18:21], v[178:181], v[202:205], v[18:21]
	v_mfma_f32_16x16x32_bf16 v[18:21], v[174:177], v[198:201], v[18:21]
	v_mfma_f32_16x16x32_bf16 v[34:37], v[174:177], v[190:193], v[34:37]
	v_mfma_f32_16x16x32_bf16 v[34:37], v[178:181], v[194:197], v[34:37]
	v_mfma_f32_16x16x32_bf16 v[50:53], v[178:181], v[186:189], v[50:53]
	v_mfma_f32_16x16x32_bf16 v[50:53], v[174:177], v[182:185], v[50:53]
	s_barrier
	s_add_u32 s75, s75, 0x100
	s_addc_u32 s76, s76, 0
	s_cmp_ge_i32 s77, s57
	s_mov_b64 s[22:23], s[24:25]
	s_mov_b32 s26, s77
	s_cbranch_scc0 .LBB0_468

.LBB0_599:
	v_add_u32_e32 v142, s74, v199
	v_add_u32_e32 v162, s75, v199
	ds_read_b128 v[130:133], v142
	ds_read_b128 v[134:137], v142 offset:1024
	ds_read_b128 v[138:141], v142 offset:2048
	ds_read_b128 v[142:145], v142 offset:3072
	ds_read_b128 v[146:149], v162
	ds_read_b128 v[150:153], v162 offset:1024
	ds_read_b128 v[174:177], v162 offset:2048
	ds_read_b128 v[178:181], v162 offset:3072
	s_add_i32 s31, s52, 2
	s_add_u32 s50, s34, 0x3ff000
	s_addc_u32 s51, s35, 0
	s_cmp_eq_u32 s71, s52
	s_cselect_b32 s56, s26, s50
	s_cselect_b32 s57, s27, s51
	s_cselect_b32 s54, s28, s23
	s_cselect_b32 s55, s29, s25
	s_add_u32 s52, s56, 0x400000
	s_addc_u32 s53, s57, 0
	s_add_i32 m0, s59, 0xc000
	ds_read_b128 v[182:185], v200
	ds_read_b128 v[186:189], v200 offset:1024
	ds_read_b128 v[190:193], v200 offset:2048
	ds_read_b128 v[194:197], v200 offset:3072
	ds_read_b128 v[202:205], v200 offset:4096
	ds_read_b128 v[206:209], v200 offset:5120
	ds_read_b128 v[210:213], v200 offset:6144
	ds_read_b128 v[214:217], v200 offset:7168
	global_load_lds_dwordx4 v164, s[34:35]
	s_add_i32 m0, s59, 0xe000
	s_nop 0
	global_load_lds_dwordx4 v166, s[34:35]
	s_waitcnt vmcnt(8)
	s_waitcnt lgkmcnt(0)
	s_barrier
	v_mfma_f32_16x16x32_bf16 v[118:121], v[130:133], v[182:185], v[118:121]
	v_mfma_f32_16x16x32_bf16 v[118:121], v[134:137], v[186:189], v[118:121]
	v_mfma_f32_16x16x32_bf16 v[110:113], v[134:137], v[194:197], v[110:113]
	v_mfma_f32_16x16x32_bf16 v[110:113], v[130:133], v[190:193], v[110:113]
	v_mfma_f32_16x16x32_bf16 v[94:97], v[130:133], v[202:205], v[94:97]
	v_mfma_f32_16x16x32_bf16 v[94:97], v[134:137], v[206:209], v[94:97]
	v_mfma_f32_16x16x32_bf16 v[78:81], v[134:137], v[214:217], v[78:81]
	v_mfma_f32_16x16x32_bf16 v[78:81], v[130:133], v[210:213], v[78:81]
	v_mfma_f32_16x16x32_bf16 v[74:77], v[138:141], v[210:213], v[74:77]
	v_mfma_f32_16x16x32_bf16 v[74:77], v[142:145], v[214:217], v[74:77]
	v_mfma_f32_16x16x32_bf16 v[90:93], v[142:145], v[206:209], v[90:93]
	v_mfma_f32_16x16x32_bf16 v[90:93], v[138:141], v[202:205], v[90:93]
	v_mfma_f32_16x16x32_bf16 v[106:109], v[138:141], v[190:193], v[106:109]
	v_mfma_f32_16x16x32_bf16 v[106:109], v[142:145], v[194:197], v[106:109]
	v_mfma_f32_16x16x32_bf16 v[122:125], v[142:145], v[186:189], v[122:125]
	v_mfma_f32_16x16x32_bf16 v[122:125], v[138:141], v[182:185], v[122:125]
	v_mfma_f32_16x16x32_bf16 v[126:129], v[146:149], v[182:185], v[126:129]
	v_mfma_f32_16x16x32_bf16 v[126:129], v[150:153], v[186:189], v[126:129]
	v_mfma_f32_16x16x32_bf16 v[102:105], v[150:153], v[194:197], v[102:105]
	v_mfma_f32_16x16x32_bf16 v[102:105], v[146:149], v[190:193], v[102:105]
	v_mfma_f32_16x16x32_bf16 v[86:89], v[146:149], v[202:205], v[86:89]
	v_mfma_f32_16x16x32_bf16 v[86:89], v[150:153], v[206:209], v[86:89]
	v_mfma_f32_16x16x32_bf16 v[70:73], v[150:153], v[214:217], v[70:73]
	v_mfma_f32_16x16x32_bf16 v[70:73], v[146:149], v[210:213], v[70:73]
	v_mfma_f32_16x16x32_bf16 v[66:69], v[174:177], v[210:213], v[66:69]
	v_mfma_f32_16x16x32_bf16 v[66:69], v[178:181], v[214:217], v[66:69]
	v_mfma_f32_16x16x32_bf16 v[82:85], v[178:181], v[206:209], v[82:85]
	v_mfma_f32_16x16x32_bf16 v[82:85], v[174:177], v[202:205], v[82:85]
	v_mfma_f32_16x16x32_bf16 v[98:101], v[174:177], v[190:193], v[98:101]
	v_mfma_f32_16x16x32_bf16 v[98:101], v[178:181], v[194:197], v[98:101]
	v_mfma_f32_16x16x32_bf16 v[114:117], v[178:181], v[186:189], v[114:117]
	v_mfma_f32_16x16x32_bf16 v[114:117], v[174:177], v[182:185], v[114:117]
	s_barrier
	s_nop 0
	s_add_i32 s50, s74, s41
	s_mov_b32 m0, s50
	ds_read_b128 v[182:185], v200 offset:16384
	ds_read_b128 v[186:189], v200 offset:17408
	ds_read_b128 v[190:193], v200 offset:18432
	ds_read_b128 v[194:197], v200 offset:19456
	ds_read_b128 v[202:205], v200 offset:20480
	ds_read_b128 v[206:209], v200 offset:21504
	ds_read_b128 v[210:213], v200 offset:22528
	ds_read_b128 v[214:217], v200 offset:23552
	global_load_lds_dwordx4 v156, s[54:55]
	s_add_i32 m0, s50, 0x2000
	s_add_u32 s50, s54, 0x20000
	v_lshl_add_u64 v[220:221], s[54:55], 0, v[160:161]
	s_addc_u32 s51, s55, 0
	s_add_i32 s78, s75, s41
	global_load_lds_dwordx4 v160, s[54:55]
	s_mov_b32 m0, s78
	s_nop 0
	global_load_lds_dwordx4 v156, s[50:51]
	s_add_i32 m0, s78, 0x2000
	s_nop 0
	global_load_lds_dwordx4 v160, s[50:51]
	s_mov_b32 m0, s59
	s_nop 0
	global_load_lds_dwordx4 v154, s[56:57]
	s_mov_b32 m0, s60
	s_nop 0
	global_load_lds_dwordx4 v158, s[56:57]
	s_waitcnt vmcnt(8)
	s_waitcnt lgkmcnt(0)
	s_barrier
	v_mfma_f32_16x16x32_bf16 v[62:65], v[130:133], v[182:185], v[62:65]
	v_mfma_f32_16x16x32_bf16 v[62:65], v[134:137], v[186:189], v[62:65]
	v_mfma_f32_16x16x32_bf16 v[46:49], v[134:137], v[194:197], v[46:49]
	v_mfma_f32_16x16x32_bf16 v[46:49], v[130:133], v[190:193], v[46:49]
	v_mfma_f32_16x16x32_bf16 v[30:33], v[130:133], v[202:205], v[30:33]
	v_mfma_f32_16x16x32_bf16 v[30:33], v[134:137], v[206:209], v[30:33]
	v_mfma_f32_16x16x32_bf16 v[14:17], v[134:137], v[214:217], v[14:17]
	v_mfma_f32_16x16x32_bf16 v[14:17], v[130:133], v[210:213], v[14:17]
	v_mfma_f32_16x16x32_bf16 v[10:13], v[138:141], v[210:213], v[10:13]
	v_mfma_f32_16x16x32_bf16 v[10:13], v[142:145], v[214:217], v[10:13]
	v_mfma_f32_16x16x32_bf16 v[26:29], v[142:145], v[206:209], v[26:29]
	v_mfma_f32_16x16x32_bf16 v[26:29], v[138:141], v[202:205], v[26:29]
	v_mfma_f32_16x16x32_bf16 v[42:45], v[138:141], v[190:193], v[42:45]
	v_mfma_f32_16x16x32_bf16 v[42:45], v[142:145], v[194:197], v[42:45]
	v_mfma_f32_16x16x32_bf16 v[58:61], v[142:145], v[186:189], v[58:61]
	v_mfma_f32_16x16x32_bf16 v[58:61], v[138:141], v[182:185], v[58:61]
	v_mfma_f32_16x16x32_bf16 v[54:57], v[146:149], v[182:185], v[54:57]
	v_mfma_f32_16x16x32_bf16 v[54:57], v[150:153], v[186:189], v[54:57]
	v_mfma_f32_16x16x32_bf16 v[38:41], v[150:153], v[194:197], v[38:41]
	v_mfma_f32_16x16x32_bf16 v[38:41], v[146:149], v[190:193], v[38:41]
	v_mfma_f32_16x16x32_bf16 v[22:25], v[146:149], v[202:205], v[22:25]
	v_mfma_f32_16x16x32_bf16 v[22:25], v[150:153], v[206:209], v[22:25]
	v_mfma_f32_16x16x32_bf16 v[6:9], v[150:153], v[214:217], v[6:9]
	v_mfma_f32_16x16x32_bf16 v[6:9], v[146:149], v[210:213], v[6:9]
	v_mfma_f32_16x16x32_bf16 v[2:5], v[174:177], v[210:213], v[2:5]
	v_mfma_f32_16x16x32_bf16 v[2:5], v[178:181], v[214:217], v[2:5]
	v_mfma_f32_16x16x32_bf16 v[18:21], v[178:181], v[206:209], v[18:21]
	v_mfma_f32_16x16x32_bf16 v[18:21], v[174:177], v[202:205], v[18:21]
	v_mfma_f32_16x16x32_bf16 v[34:37], v[174:177], v[190:193], v[34:37]
	v_mfma_f32_16x16x32_bf16 v[34:37], v[178:181], v[194:197], v[34:37]
	v_mfma_f32_16x16x32_bf16 v[50:53], v[178:181], v[186:189], v[50:53]
	v_mfma_f32_16x16x32_bf16 v[50:53], v[174:177], v[182:185], v[50:53]
	s_barrier
	s_add_i32 s78, 0, 0x18000
	s_add_i32 s79, 0, 0x1c000
	v_add_u32_e32 v142, s78, v199
	v_add_u32_e32 v162, s79, v199
	ds_read_b128 v[130:133], v142
	ds_read_b128 v[134:137], v142 offset:1024
	ds_read_b128 v[138:141], v142 offset:2048
	ds_read_b128 v[142:145], v142 offset:3072
	ds_read_b128 v[146:149], v162
	ds_read_b128 v[150:153], v162 offset:1024
	ds_read_b128 v[174:177], v162 offset:2048
	ds_read_b128 v[178:181], v162 offset:3072
	s_add_u32 s50, s56, 0x1000
	s_addc_u32 s51, s57, 0
	s_mov_b32 m0, s61
	ds_read_b128 v[182:185], v200 offset:32768
	ds_read_b128 v[186:189], v200 offset:33792
	ds_read_b128 v[190:193], v200 offset:34816
	ds_read_b128 v[194:197], v200 offset:35840
	ds_read_b128 v[202:205], v200 offset:36864
	ds_read_b128 v[206:209], v200 offset:37888
	ds_read_b128 v[210:213], v200 offset:38912
	ds_read_b128 v[214:217], v200 offset:39936
	global_load_lds_dwordx4 v154, s[50:51]
	s_mov_b32 m0, s62
	s_nop 0
	global_load_lds_dwordx4 v158, s[50:51]
	s_waitcnt vmcnt(8)
	s_waitcnt lgkmcnt(0)
	s_barrier
	v_mfma_f32_16x16x32_bf16 v[118:121], v[130:133], v[182:185], v[118:121]
	v_mfma_f32_16x16x32_bf16 v[118:121], v[134:137], v[186:189], v[118:121]
	v_mfma_f32_16x16x32_bf16 v[110:113], v[134:137], v[194:197], v[110:113]
	v_mfma_f32_16x16x32_bf16 v[110:113], v[130:133], v[190:193], v[110:113]
	v_mfma_f32_16x16x32_bf16 v[94:97], v[130:133], v[202:205], v[94:97]
	v_mfma_f32_16x16x32_bf16 v[94:97], v[134:137], v[206:209], v[94:97]
	v_mfma_f32_16x16x32_bf16 v[78:81], v[134:137], v[214:217], v[78:81]
	v_mfma_f32_16x16x32_bf16 v[78:81], v[130:133], v[210:213], v[78:81]
	v_mfma_f32_16x16x32_bf16 v[74:77], v[138:141], v[210:213], v[74:77]
	v_mfma_f32_16x16x32_bf16 v[74:77], v[142:145], v[214:217], v[74:77]
	v_mfma_f32_16x16x32_bf16 v[90:93], v[142:145], v[206:209], v[90:93]
	v_mfma_f32_16x16x32_bf16 v[90:93], v[138:141], v[202:205], v[90:93]
	v_mfma_f32_16x16x32_bf16 v[106:109], v[138:141], v[190:193], v[106:109]
	v_mfma_f32_16x16x32_bf16 v[106:109], v[142:145], v[194:197], v[106:109]
	v_mfma_f32_16x16x32_bf16 v[122:125], v[142:145], v[186:189], v[122:125]
	v_mfma_f32_16x16x32_bf16 v[122:125], v[138:141], v[182:185], v[122:125]
	v_mfma_f32_16x16x32_bf16 v[126:129], v[146:149], v[182:185], v[126:129]
	v_mfma_f32_16x16x32_bf16 v[126:129], v[150:153], v[186:189], v[126:129]
	v_mfma_f32_16x16x32_bf16 v[102:105], v[150:153], v[194:197], v[102:105]
	v_mfma_f32_16x16x32_bf16 v[102:105], v[146:149], v[190:193], v[102:105]
	v_mfma_f32_16x16x32_bf16 v[86:89], v[146:149], v[202:205], v[86:89]
	v_mfma_f32_16x16x32_bf16 v[86:89], v[150:153], v[206:209], v[86:89]
	v_mfma_f32_16x16x32_bf16 v[70:73], v[150:153], v[214:217], v[70:73]
	v_mfma_f32_16x16x32_bf16 v[70:73], v[146:149], v[210:213], v[70:73]
	v_mfma_f32_16x16x32_bf16 v[66:69], v[174:177], v[210:213], v[66:69]
	v_mfma_f32_16x16x32_bf16 v[66:69], v[178:181], v[214:217], v[66:69]
	v_mfma_f32_16x16x32_bf16 v[82:85], v[178:181], v[206:209], v[82:85]
	v_mfma_f32_16x16x32_bf16 v[82:85], v[174:177], v[202:205], v[82:85]
	v_mfma_f32_16x16x32_bf16 v[98:101], v[174:177], v[190:193], v[98:101]
	v_mfma_f32_16x16x32_bf16 v[98:101], v[178:181], v[194:197], v[98:101]
	v_mfma_f32_16x16x32_bf16 v[114:117], v[178:181], v[186:189], v[114:117]
	v_mfma_f32_16x16x32_bf16 v[114:117], v[174:177], v[182:185], v[114:117]
	s_barrier
	s_nop 0
	s_add_i32 s50, s78, s41
	s_mov_b32 m0, s50
	ds_read_b128 v[182:185], v200 offset:49152
	ds_read_b128 v[186:189], v200 offset:50176
	ds_read_b128 v[190:193], v200 offset:51200
	ds_read_b128 v[194:197], v200 offset:52224
	ds_read_b128 v[202:205], v200 offset:53248
	ds_read_b128 v[206:209], v200 offset:54272
	ds_read_b128 v[210:213], v200 offset:55296
	ds_read_b128 v[214:217], v200 offset:56320
	s_add_u32 s98, s54, s14
	s_addc_u32 s99, s55, s15
	global_load_lds_dwordx4 v156, s[98:99]
	s_add_i32 m0, s50, 0x2000
	s_add_u32 s50, s54, 0x20080
	v_lshl_add_u64 v[218:219], v[220:221], 0, s[14:15]
	s_addc_u32 s51, s55, 0
	s_add_i32 s54, s79, s41
	global_load_lds_dwordx4 v[218:219], off
	s_mov_b32 m0, s54
	s_nop 0
	global_load_lds_dwordx4 v156, s[50:51]
	s_add_i32 m0, s54, 0x2000
	s_nop 0
	global_load_lds_dwordx4 v160, s[50:51]
	s_mov_b32 m0, s69
	s_nop 0
	global_load_lds_dwordx4 v154, s[52:53]
	s_mov_b32 m0, s70
	s_nop 0
	global_load_lds_dwordx4 v158, s[52:53]
	s_waitcnt vmcnt(8)
	s_waitcnt lgkmcnt(0)
	s_barrier
	v_mfma_f32_16x16x32_bf16 v[62:65], v[130:133], v[182:185], v[62:65]
	v_mfma_f32_16x16x32_bf16 v[62:65], v[134:137], v[186:189], v[62:65]
	v_mfma_f32_16x16x32_bf16 v[46:49], v[134:137], v[194:197], v[46:49]
	v_mfma_f32_16x16x32_bf16 v[46:49], v[130:133], v[190:193], v[46:49]
	v_mfma_f32_16x16x32_bf16 v[30:33], v[130:133], v[202:205], v[30:33]
	v_mfma_f32_16x16x32_bf16 v[30:33], v[134:137], v[206:209], v[30:33]
	v_mfma_f32_16x16x32_bf16 v[14:17], v[134:137], v[214:217], v[14:17]
	v_mfma_f32_16x16x32_bf16 v[14:17], v[130:133], v[210:213], v[14:17]
	v_mfma_f32_16x16x32_bf16 v[10:13], v[138:141], v[210:213], v[10:13]
	v_mfma_f32_16x16x32_bf16 v[10:13], v[142:145], v[214:217], v[10:13]
	v_mfma_f32_16x16x32_bf16 v[26:29], v[142:145], v[206:209], v[26:29]
	v_mfma_f32_16x16x32_bf16 v[26:29], v[138:141], v[202:205], v[26:29]
	v_mfma_f32_16x16x32_bf16 v[42:45], v[138:141], v[190:193], v[42:45]
	v_mfma_f32_16x16x32_bf16 v[42:45], v[142:145], v[194:197], v[42:45]
	v_mfma_f32_16x16x32_bf16 v[58:61], v[142:145], v[186:189], v[58:61]
	v_mfma_f32_16x16x32_bf16 v[58:61], v[138:141], v[182:185], v[58:61]
	v_mfma_f32_16x16x32_bf16 v[54:57], v[146:149], v[182:185], v[54:57]
	v_mfma_f32_16x16x32_bf16 v[54:57], v[150:153], v[186:189], v[54:57]
	v_mfma_f32_16x16x32_bf16 v[38:41], v[150:153], v[194:197], v[38:41]
	v_mfma_f32_16x16x32_bf16 v[38:41], v[146:149], v[190:193], v[38:41]
	v_mfma_f32_16x16x32_bf16 v[22:25], v[146:149], v[202:205], v[22:25]
	v_mfma_f32_16x16x32_bf16 v[22:25], v[150:153], v[206:209], v[22:25]
	v_mfma_f32_16x16x32_bf16 v[6:9], v[150:153], v[214:217], v[6:9]
	v_mfma_f32_16x16x32_bf16 v[6:9], v[146:149], v[210:213], v[6:9]
	v_mfma_f32_16x16x32_bf16 v[2:5], v[174:177], v[210:213], v[2:5]
	v_mfma_f32_16x16x32_bf16 v[2:5], v[178:181], v[214:217], v[2:5]
	v_mfma_f32_16x16x32_bf16 v[18:21], v[178:181], v[206:209], v[18:21]
	v_mfma_f32_16x16x32_bf16 v[18:21], v[174:177], v[202:205], v[18:21]
	v_mfma_f32_16x16x32_bf16 v[34:37], v[174:177], v[190:193], v[34:37]
	v_mfma_f32_16x16x32_bf16 v[34:37], v[178:181], v[194:197], v[34:37]
	v_mfma_f32_16x16x32_bf16 v[50:53], v[178:181], v[186:189], v[50:53]
	v_mfma_f32_16x16x32_bf16 v[50:53], v[174:177], v[182:185], v[50:53]
	s_barrier
	s_add_u32 s23, s23, 0x100
	s_addc_u32 s25, s25, 0
	s_add_u32 s34, s34, 0x800000
	s_addc_u32 s35, s35, 0
	s_cmp_ge_i32 s31, s67
	s_mov_b32 s52, s31
	s_cbranch_scc0 .LBB0_599

.LBB0_740:
	s_nop 0
	v_add_u32_e32 v144, s88, v188
	v_add_u32_e32 v160, s89, v188
	ds_read_b128 v[132:135], v144
	ds_read_b128 v[136:139], v144 offset:1024
	ds_read_b128 v[140:143], v144 offset:2048
	ds_read_b128 v[144:147], v144 offset:3072
	ds_read_b128 v[148:151], v160
	ds_read_b128 v[152:155], v160 offset:1024
	ds_read_b128 v[156:159], v160 offset:2048
	ds_read_b128 v[184:187], v160 offset:3072
	s_add_i32 s92, s55, 2
	s_add_u32 s50, s60, 0x3fc000
	s_addc_u32 s51, s61, 0
	s_cmp_eq_u32 s87, s55
	s_cselect_b32 s70, s64, s50
	s_cselect_b32 s71, s65, s51
	s_cselect_b32 s69, s67, s53
	s_cselect_b32 s68, s66, s13
	s_add_u32 s62, s70, 0x400000
	s_addc_u32 s63, s71, 0
	s_add_i32 m0, s77, 0xc000
	ds_read_b128 v[192:195], v189
	ds_read_b128 v[196:199], v189 offset:1024
	ds_read_b128 v[200:203], v189 offset:2048
	ds_read_b128 v[204:207], v189 offset:3072
	ds_read_b128 v[208:211], v189 offset:4096
	ds_read_b128 v[212:215], v189 offset:5120
	ds_read_b128 v[216:219], v189 offset:6144
	ds_read_b128 v[220:223], v189 offset:7168
	global_load_lds_dwordx4 v176, s[60:61]
	s_add_i32 m0, s77, 0xe000
	s_nop 0
	global_load_lds_dwordx4 v178, s[60:61]
	s_waitcnt vmcnt(8)
	s_waitcnt lgkmcnt(0)
	s_barrier
	v_mfma_f32_16x16x32_bf16 v[30:33], v[132:135], v[192:195], v[30:33]
	v_mfma_f32_16x16x32_bf16 v[30:33], v[136:139], v[196:199], v[30:33]
	v_mfma_f32_16x16x32_bf16 v[86:89], v[136:139], v[204:207], v[86:89]
	v_mfma_f32_16x16x32_bf16 v[86:89], v[132:135], v[200:203], v[86:89]
	v_mfma_f32_16x16x32_bf16 v[94:97], v[132:135], v[208:211], v[94:97]
	v_mfma_f32_16x16x32_bf16 v[94:97], v[136:139], v[212:215], v[94:97]
	v_mfma_f32_16x16x32_bf16 v[90:93], v[136:139], v[220:223], v[90:93]
	v_mfma_f32_16x16x32_bf16 v[90:93], v[132:135], v[216:219], v[90:93]
	v_mfma_f32_16x16x32_bf16 v[78:81], v[140:143], v[216:219], v[78:81]
	v_mfma_f32_16x16x32_bf16 v[78:81], v[144:147], v[220:223], v[78:81]
	v_mfma_f32_16x16x32_bf16 v[82:85], v[144:147], v[212:215], v[82:85]
	v_mfma_f32_16x16x32_bf16 v[82:85], v[140:143], v[208:211], v[82:85]
	v_mfma_f32_16x16x32_bf16 v[66:69], v[140:143], v[200:203], v[66:69]
	v_mfma_f32_16x16x32_bf16 v[66:69], v[144:147], v[204:207], v[66:69]
	v_mfma_f32_16x16x32_bf16 v[26:29], v[144:147], v[196:199], v[26:29]
	v_mfma_f32_16x16x32_bf16 v[26:29], v[140:143], v[192:195], v[26:29]
	v_mfma_f32_16x16x32_bf16 v[50:53], v[148:151], v[192:195], v[50:53]
	v_mfma_f32_16x16x32_bf16 v[50:53], v[152:155], v[196:199], v[50:53]
	v_mfma_f32_16x16x32_bf16 v[14:17], v[152:155], v[204:207], v[14:17]
	v_mfma_f32_16x16x32_bf16 v[14:17], v[148:151], v[200:203], v[14:17]
	v_mfma_f32_16x16x32_bf16 v[22:25], v[148:151], v[208:211], v[22:25]
	v_mfma_f32_16x16x32_bf16 v[22:25], v[152:155], v[212:215], v[22:25]
	v_mfma_f32_16x16x32_bf16 v[18:21], v[152:155], v[220:223], v[18:21]
	v_mfma_f32_16x16x32_bf16 v[18:21], v[148:151], v[216:219], v[18:21]
	v_mfma_f32_16x16x32_bf16 v[6:9], v[156:159], v[216:219], v[6:9]
	v_mfma_f32_16x16x32_bf16 v[6:9], v[184:187], v[220:223], v[6:9]
	v_mfma_f32_16x16x32_bf16 v[10:13], v[184:187], v[212:215], v[10:13]
	v_mfma_f32_16x16x32_bf16 v[10:13], v[156:159], v[208:211], v[10:13]
	v_mfma_f32_16x16x32_bf16 v[2:5], v[156:159], v[200:203], v[2:5]
	v_mfma_f32_16x16x32_bf16 v[2:5], v[184:187], v[204:207], v[2:5]
	v_mfma_f32_16x16x32_bf16 v[42:45], v[184:187], v[196:199], v[42:45]
	v_mfma_f32_16x16x32_bf16 v[42:45], v[156:159], v[192:195], v[42:45]
	s_barrier
	s_nop 0
	s_add_i32 s50, s88, s76
	s_mov_b32 m0, s50
	ds_read_b128 v[192:195], v189 offset:16384
	ds_read_b128 v[196:199], v189 offset:17408
	ds_read_b128 v[200:203], v189 offset:18432
	ds_read_b128 v[204:207], v189 offset:19456
	ds_read_b128 v[208:211], v189 offset:20480
	ds_read_b128 v[212:215], v189 offset:21504
	ds_read_b128 v[216:219], v189 offset:22528
	ds_read_b128 v[220:223], v189 offset:23552
	global_load_lds_dwordx4 v164, s[68:69]
	s_add_i32 m0, s50, 0x2000
	s_add_u32 s50, s68, 0x10000
	s_addc_u32 s51, s69, 0
	s_add_i32 s55, s89, s76
	global_load_lds_dwordx4 v168, s[68:69]
	s_mov_b32 m0, s55
	s_nop 0
	global_load_lds_dwordx4 v164, s[50:51]
	s_add_i32 m0, s55, 0x2000
	s_nop 0
	global_load_lds_dwordx4 v168, s[50:51]
	s_mov_b32 m0, s77
	s_nop 0
	global_load_lds_dwordx4 v162, s[70:71]
	s_mov_b32 m0, s78
	s_nop 0
	global_load_lds_dwordx4 v166, s[70:71]
	s_waitcnt vmcnt(8)
	s_waitcnt lgkmcnt(0)
	s_barrier
	v_mfma_f32_16x16x32_bf16 v[118:121], v[132:135], v[192:195], v[118:121]
	v_mfma_f32_16x16x32_bf16 v[118:121], v[136:139], v[196:199], v[118:121]
	v_mfma_f32_16x16x32_bf16 v[114:117], v[136:139], v[204:207], v[114:117]
	v_mfma_f32_16x16x32_bf16 v[114:117], v[132:135], v[200:203], v[114:117]
	v_mfma_f32_16x16x32_bf16 v[126:129], v[132:135], v[208:211], v[126:129]
	v_mfma_f32_16x16x32_bf16 v[126:129], v[136:139], v[212:215], v[126:129]
	v_mfma_f32_16x16x32_bf16 v[122:125], v[136:139], v[220:223], v[122:125]
	v_mfma_f32_16x16x32_bf16 v[122:125], v[132:135], v[216:219], v[122:125]
	v_mfma_f32_16x16x32_bf16 v[106:109], v[140:143], v[216:219], v[106:109]
	v_mfma_f32_16x16x32_bf16 v[106:109], v[144:147], v[220:223], v[106:109]
	v_mfma_f32_16x16x32_bf16 v[110:113], v[144:147], v[212:215], v[110:113]
	v_mfma_f32_16x16x32_bf16 v[110:113], v[140:143], v[208:211], v[110:113]
	v_mfma_f32_16x16x32_bf16 v[98:101], v[140:143], v[200:203], v[98:101]
	v_mfma_f32_16x16x32_bf16 v[98:101], v[144:147], v[204:207], v[98:101]
	v_mfma_f32_16x16x32_bf16 v[102:105], v[144:147], v[196:199], v[102:105]
	v_mfma_f32_16x16x32_bf16 v[102:105], v[140:143], v[192:195], v[102:105]
	v_mfma_f32_16x16x32_bf16 v[62:65], v[148:151], v[192:195], v[62:65]
	v_mfma_f32_16x16x32_bf16 v[62:65], v[152:155], v[196:199], v[62:65]
	v_mfma_f32_16x16x32_bf16 v[58:61], v[152:155], v[204:207], v[58:61]
	v_mfma_f32_16x16x32_bf16 v[58:61], v[148:151], v[200:203], v[58:61]
	v_mfma_f32_16x16x32_bf16 v[74:77], v[148:151], v[208:211], v[74:77]
	v_mfma_f32_16x16x32_bf16 v[74:77], v[152:155], v[212:215], v[74:77]
	v_mfma_f32_16x16x32_bf16 v[70:73], v[152:155], v[220:223], v[70:73]
	v_mfma_f32_16x16x32_bf16 v[70:73], v[148:151], v[216:219], v[70:73]
	v_mfma_f32_16x16x32_bf16 v[46:49], v[156:159], v[216:219], v[46:49]
	v_mfma_f32_16x16x32_bf16 v[46:49], v[184:187], v[220:223], v[46:49]
	v_mfma_f32_16x16x32_bf16 v[54:57], v[184:187], v[212:215], v[54:57]
	v_mfma_f32_16x16x32_bf16 v[54:57], v[156:159], v[208:211], v[54:57]
	v_mfma_f32_16x16x32_bf16 v[34:37], v[156:159], v[200:203], v[34:37]
	v_mfma_f32_16x16x32_bf16 v[34:37], v[184:187], v[204:207], v[34:37]
	v_mfma_f32_16x16x32_bf16 v[38:41], v[184:187], v[196:199], v[38:41]
	v_mfma_f32_16x16x32_bf16 v[38:41], v[156:159], v[192:195], v[38:41]
	s_barrier
	s_add_i32 s55, 0, 0x18000
	s_add_i32 s93, 0, 0x1c000
	v_add_u32_e32 v144, s55, v188
	v_add_u32_e32 v184, s93, v188
	ds_read_b128 v[132:135], v144
	ds_read_b128 v[136:139], v144 offset:1024
	ds_read_b128 v[140:143], v144 offset:2048
	ds_read_b128 v[144:147], v144 offset:3072
	ds_read_b128 v[148:151], v184
	ds_read_b128 v[152:155], v184 offset:1024
	ds_read_b128 v[156:159], v184 offset:2048
	ds_read_b128 v[184:187], v184 offset:3072
	s_add_u32 s50, s70, 0x4000
	s_addc_u32 s51, s71, 0
	s_mov_b32 m0, s79
	ds_read_b128 v[192:195], v189 offset:32768
	ds_read_b128 v[196:199], v189 offset:33792
	ds_read_b128 v[200:203], v189 offset:34816
	ds_read_b128 v[204:207], v189 offset:35840
	ds_read_b128 v[208:211], v189 offset:36864
	ds_read_b128 v[212:215], v189 offset:37888
	ds_read_b128 v[216:219], v189 offset:38912
	ds_read_b128 v[220:223], v189 offset:39936
	global_load_lds_dwordx4 v162, s[50:51]
	s_mov_b32 m0, s80
	s_nop 0
	global_load_lds_dwordx4 v166, s[50:51]
	s_waitcnt vmcnt(8)
	s_waitcnt lgkmcnt(0)
	s_barrier
	v_mfma_f32_16x16x32_bf16 v[30:33], v[132:135], v[192:195], v[30:33]
	v_mfma_f32_16x16x32_bf16 v[30:33], v[136:139], v[196:199], v[30:33]
	v_mfma_f32_16x16x32_bf16 v[86:89], v[136:139], v[204:207], v[86:89]
	v_mfma_f32_16x16x32_bf16 v[86:89], v[132:135], v[200:203], v[86:89]
	v_mfma_f32_16x16x32_bf16 v[94:97], v[132:135], v[208:211], v[94:97]
	v_mfma_f32_16x16x32_bf16 v[94:97], v[136:139], v[212:215], v[94:97]
	v_mfma_f32_16x16x32_bf16 v[90:93], v[136:139], v[220:223], v[90:93]
	v_mfma_f32_16x16x32_bf16 v[90:93], v[132:135], v[216:219], v[90:93]
	v_mfma_f32_16x16x32_bf16 v[78:81], v[140:143], v[216:219], v[78:81]
	v_mfma_f32_16x16x32_bf16 v[78:81], v[144:147], v[220:223], v[78:81]
	v_mfma_f32_16x16x32_bf16 v[82:85], v[144:147], v[212:215], v[82:85]
	v_mfma_f32_16x16x32_bf16 v[82:85], v[140:143], v[208:211], v[82:85]
	v_mfma_f32_16x16x32_bf16 v[66:69], v[140:143], v[200:203], v[66:69]
	v_mfma_f32_16x16x32_bf16 v[66:69], v[144:147], v[204:207], v[66:69]
	v_mfma_f32_16x16x32_bf16 v[26:29], v[144:147], v[196:199], v[26:29]
	v_mfma_f32_16x16x32_bf16 v[26:29], v[140:143], v[192:195], v[26:29]
	v_mfma_f32_16x16x32_bf16 v[50:53], v[148:151], v[192:195], v[50:53]
	v_mfma_f32_16x16x32_bf16 v[50:53], v[152:155], v[196:199], v[50:53]
	v_mfma_f32_16x16x32_bf16 v[14:17], v[152:155], v[204:207], v[14:17]
	v_mfma_f32_16x16x32_bf16 v[14:17], v[148:151], v[200:203], v[14:17]
	v_mfma_f32_16x16x32_bf16 v[22:25], v[148:151], v[208:211], v[22:25]
	v_mfma_f32_16x16x32_bf16 v[22:25], v[152:155], v[212:215], v[22:25]
	v_mfma_f32_16x16x32_bf16 v[18:21], v[152:155], v[220:223], v[18:21]
	v_mfma_f32_16x16x32_bf16 v[18:21], v[148:151], v[216:219], v[18:21]
	v_mfma_f32_16x16x32_bf16 v[6:9], v[156:159], v[216:219], v[6:9]
	v_mfma_f32_16x16x32_bf16 v[6:9], v[184:187], v[220:223], v[6:9]
	v_mfma_f32_16x16x32_bf16 v[10:13], v[184:187], v[212:215], v[10:13]
	v_mfma_f32_16x16x32_bf16 v[10:13], v[156:159], v[208:211], v[10:13]
	v_mfma_f32_16x16x32_bf16 v[2:5], v[156:159], v[200:203], v[2:5]
	v_mfma_f32_16x16x32_bf16 v[2:5], v[184:187], v[204:207], v[2:5]
	v_mfma_f32_16x16x32_bf16 v[42:45], v[184:187], v[196:199], v[42:45]
	v_mfma_f32_16x16x32_bf16 v[42:45], v[156:159], v[192:195], v[42:45]
	s_barrier
	s_nop 0
	s_add_i32 s50, s55, s76
	s_mov_b32 m0, s50
	ds_read_b128 v[192:195], v189 offset:49152
	ds_read_b128 v[196:199], v189 offset:50176
	ds_read_b128 v[200:203], v189 offset:51200
	ds_read_b128 v[204:207], v189 offset:52224
	ds_read_b128 v[208:211], v189 offset:53248
	ds_read_b128 v[212:215], v189 offset:54272
	ds_read_b128 v[216:219], v189 offset:55296
	ds_read_b128 v[220:223], v189 offset:56320
	s_add_u32 s98, s68, s14
	s_addc_u32 s99, s69, s15
	global_load_lds_dwordx4 v164, s[98:99]
	s_add_i32 m0, s50, 0x2000
	s_add_u32 s50, s68, 0x10080
	s_addc_u32 s51, s69, 0
	s_add_i32 s55, s93, s76
	s_add_u32 s100, s68, s14
	s_addc_u32 s101, s69, s15
	global_load_lds_dwordx4 v168, s[100:101]
	s_mov_b32 m0, s55
	s_nop 0
	global_load_lds_dwordx4 v164, s[50:51]
	s_add_i32 m0, s55, 0x2000
	s_nop 0
	global_load_lds_dwordx4 v168, s[50:51]
	s_mov_b32 m0, s84
	s_nop 0
	global_load_lds_dwordx4 v162, s[62:63]
	s_mov_b32 m0, s85
	s_nop 0
	global_load_lds_dwordx4 v166, s[62:63]
	s_waitcnt vmcnt(8)
	s_waitcnt lgkmcnt(0)
	s_barrier
	v_mfma_f32_16x16x32_bf16 v[118:121], v[132:135], v[192:195], v[118:121]
	v_mfma_f32_16x16x32_bf16 v[118:121], v[136:139], v[196:199], v[118:121]
	v_mfma_f32_16x16x32_bf16 v[114:117], v[136:139], v[204:207], v[114:117]
	v_mfma_f32_16x16x32_bf16 v[114:117], v[132:135], v[200:203], v[114:117]
	v_mfma_f32_16x16x32_bf16 v[126:129], v[132:135], v[208:211], v[126:129]
	v_mfma_f32_16x16x32_bf16 v[126:129], v[136:139], v[212:215], v[126:129]
	v_mfma_f32_16x16x32_bf16 v[122:125], v[136:139], v[220:223], v[122:125]
	v_mfma_f32_16x16x32_bf16 v[122:125], v[132:135], v[216:219], v[122:125]
	v_mfma_f32_16x16x32_bf16 v[106:109], v[140:143], v[216:219], v[106:109]
	v_mfma_f32_16x16x32_bf16 v[106:109], v[144:147], v[220:223], v[106:109]
	v_mfma_f32_16x16x32_bf16 v[110:113], v[144:147], v[212:215], v[110:113]
	v_mfma_f32_16x16x32_bf16 v[110:113], v[140:143], v[208:211], v[110:113]
	v_mfma_f32_16x16x32_bf16 v[98:101], v[140:143], v[200:203], v[98:101]
	v_mfma_f32_16x16x32_bf16 v[98:101], v[144:147], v[204:207], v[98:101]
	v_mfma_f32_16x16x32_bf16 v[102:105], v[144:147], v[196:199], v[102:105]
	v_mfma_f32_16x16x32_bf16 v[102:105], v[140:143], v[192:195], v[102:105]
	v_mfma_f32_16x16x32_bf16 v[62:65], v[148:151], v[192:195], v[62:65]
	v_mfma_f32_16x16x32_bf16 v[62:65], v[152:155], v[196:199], v[62:65]
	v_mfma_f32_16x16x32_bf16 v[58:61], v[152:155], v[204:207], v[58:61]
	v_mfma_f32_16x16x32_bf16 v[58:61], v[148:151], v[200:203], v[58:61]
	v_mfma_f32_16x16x32_bf16 v[74:77], v[148:151], v[208:211], v[74:77]
	v_mfma_f32_16x16x32_bf16 v[74:77], v[152:155], v[212:215], v[74:77]
	v_mfma_f32_16x16x32_bf16 v[70:73], v[152:155], v[220:223], v[70:73]
	v_mfma_f32_16x16x32_bf16 v[70:73], v[148:151], v[216:219], v[70:73]
	v_mfma_f32_16x16x32_bf16 v[46:49], v[156:159], v[216:219], v[46:49]
	v_mfma_f32_16x16x32_bf16 v[46:49], v[184:187], v[220:223], v[46:49]
	v_mfma_f32_16x16x32_bf16 v[54:57], v[184:187], v[212:215], v[54:57]
	v_mfma_f32_16x16x32_bf16 v[54:57], v[156:159], v[208:211], v[54:57]
	v_mfma_f32_16x16x32_bf16 v[34:37], v[156:159], v[200:203], v[34:37]
	v_mfma_f32_16x16x32_bf16 v[34:37], v[184:187], v[204:207], v[34:37]
	v_mfma_f32_16x16x32_bf16 v[38:41], v[184:187], v[196:199], v[38:41]
	v_mfma_f32_16x16x32_bf16 v[38:41], v[156:159], v[192:195], v[38:41]
	s_barrier
	s_add_u32 s13, s13, 0x100
	s_addc_u32 s53, s53, 0
	s_add_u32 s60, s60, 0x800000
	s_addc_u32 s61, s61, 0
	s_cmp_ge_i32 s92, s83
	s_cbranch_scc0 .LBB0_738

.LBB0_872:
	s_nop 0
	s_add_i32 s77, s52, 2
	s_add_u32 s50, s34, 0xfffc0080
	s_addc_u32 s51, s35, -1
	s_cmp_eq_u32 s70, s52
	s_cselect_b32 s52, s30, s21
	s_cselect_b32 s55, s29, s51
	s_cselect_b32 s54, s28, s50
	s_cselect_b32 s53, s31, s23
	ds_read_b128 v[150:153], v246
	ds_read_b128 v[154:157], v246 offset:1024
	ds_read_b128 v[158:161], v246 offset:2048
	ds_read_b128 v[162:165], v246 offset:3072
	ds_read_b128 v[166:169], v247
	ds_read_b128 v[170:173], v247 offset:1024
	ds_read_b128 v[174:177], v247 offset:2048
	ds_read_b128 v[178:181], v247 offset:3072
	ds_read_b128 v[182:185], v149
	ds_read_b128 v[186:189], v149 offset:1024
	ds_read_b128 v[190:193], v149 offset:2048
	ds_read_b128 v[194:197], v149 offset:3072
	ds_read_b128 v[198:201], v149 offset:4096
	ds_read_b128 v[202:205], v149 offset:5120
	ds_read_b128 v[206:209], v149 offset:6144
	ds_read_b128 v[210:213], v149 offset:7168
	s_add_i32 m0, s60, 0xc000
	s_nop 0
	global_load_lds_dwordx4 v132, s[34:35]
	s_add_i32 m0, s60, 0xe000
	s_nop 0
	global_load_lds_dwordx4 v134, s[34:35]
	s_waitcnt vmcnt(8)
	s_waitcnt lgkmcnt(0)
	s_barrier
	v_mfma_f32_16x16x32_bf16 v[78:81], v[150:153], v[182:185], v[78:81]
	v_mfma_f32_16x16x32_bf16 v[78:81], v[154:157], v[186:189], v[78:81]
	v_mfma_f32_16x16x32_bf16 v[66:69], v[154:157], v[194:197], v[66:69]
	v_mfma_f32_16x16x32_bf16 v[66:69], v[150:153], v[190:193], v[66:69]
	v_mfma_f32_16x16x32_bf16 v[70:73], v[150:153], v[198:201], v[70:73]
	v_mfma_f32_16x16x32_bf16 v[70:73], v[154:157], v[202:205], v[70:73]
	v_mfma_f32_16x16x32_bf16 v[74:77], v[154:157], v[210:213], v[74:77]
	v_mfma_f32_16x16x32_bf16 v[74:77], v[150:153], v[206:209], v[74:77]
	v_mfma_f32_16x16x32_bf16 v[10:13], v[158:161], v[206:209], v[10:13]
	v_mfma_f32_16x16x32_bf16 v[10:13], v[162:165], v[210:213], v[10:13]
	v_mfma_f32_16x16x32_bf16 v[6:9], v[162:165], v[202:205], v[6:9]
	v_mfma_f32_16x16x32_bf16 v[6:9], v[158:161], v[198:201], v[6:9]
	v_mfma_f32_16x16x32_bf16 v[2:5], v[158:161], v[190:193], v[2:5]
	v_mfma_f32_16x16x32_bf16 v[2:5], v[162:165], v[194:197], v[2:5]
	v_mfma_f32_16x16x32_bf16 v[14:17], v[162:165], v[186:189], v[14:17]
	v_mfma_f32_16x16x32_bf16 v[14:17], v[158:161], v[182:185], v[14:17]
	v_mfma_f32_16x16x32_bf16 v[98:101], v[166:169], v[182:185], v[98:101]
	v_mfma_f32_16x16x32_bf16 v[98:101], v[170:173], v[186:189], v[98:101]
	v_mfma_f32_16x16x32_bf16 v[82:85], v[170:173], v[194:197], v[82:85]
	v_mfma_f32_16x16x32_bf16 v[82:85], v[166:169], v[190:193], v[82:85]
	v_mfma_f32_16x16x32_bf16 v[86:89], v[166:169], v[198:201], v[86:89]
	v_mfma_f32_16x16x32_bf16 v[86:89], v[170:173], v[202:205], v[86:89]
	v_mfma_f32_16x16x32_bf16 v[94:97], v[170:173], v[210:213], v[94:97]
	v_mfma_f32_16x16x32_bf16 v[94:97], v[166:169], v[206:209], v[94:97]
	v_mfma_f32_16x16x32_bf16 v[30:33], v[174:177], v[206:209], v[30:33]
	v_mfma_f32_16x16x32_bf16 v[30:33], v[178:181], v[210:213], v[30:33]
	v_mfma_f32_16x16x32_bf16 v[22:25], v[178:181], v[202:205], v[22:25]
	v_mfma_f32_16x16x32_bf16 v[22:25], v[174:177], v[198:201], v[22:25]
	v_mfma_f32_16x16x32_bf16 v[18:21], v[174:177], v[190:193], v[18:21]
	v_mfma_f32_16x16x32_bf16 v[18:21], v[178:181], v[194:197], v[18:21]
	v_mfma_f32_16x16x32_bf16 v[34:37], v[178:181], v[186:189], v[34:37]
	v_mfma_f32_16x16x32_bf16 v[34:37], v[174:177], v[182:185], v[34:37]
	s_barrier
	ds_read_b128 v[182:185], v149 offset:16384
	ds_read_b128 v[186:189], v149 offset:17408
	ds_read_b128 v[190:193], v149 offset:18432
	ds_read_b128 v[194:197], v149 offset:19456
	ds_read_b128 v[198:201], v149 offset:20480
	ds_read_b128 v[202:205], v149 offset:21504
	ds_read_b128 v[206:209], v149 offset:22528
	ds_read_b128 v[210:213], v149 offset:23552
	s_add_i32 s50, s73, s15
	s_mov_b32 m0, s50
	s_nop 0
	global_load_lds_dwordx4 v228, s[52:53]
	s_add_i32 m0, s50, 0x2000
	s_add_u32 s50, s52, 0x40000
	s_addc_u32 s51, s53, 0
	s_add_i32 s78, s74, s15
	global_load_lds_dwordx4 v232, s[52:53]
	s_mov_b32 m0, s78
	s_nop 0
	global_load_lds_dwordx4 v228, s[50:51]
	s_add_i32 m0, s78, 0x2000
	s_nop 0
	global_load_lds_dwordx4 v232, s[50:51]
	s_mov_b32 m0, s60
	s_nop 0
	global_load_lds_dwordx4 v226, s[54:55]
	s_mov_b32 m0, s61
	s_nop 0
	global_load_lds_dwordx4 v230, s[54:55]
	s_waitcnt vmcnt(8)
	s_waitcnt lgkmcnt(0)
	s_barrier
	v_mfma_f32_16x16x32_bf16 v[90:93], v[150:153], v[182:185], v[90:93]
	v_mfma_f32_16x16x32_bf16 v[90:93], v[154:157], v[186:189], v[90:93]
	v_mfma_f32_16x16x32_bf16 v[102:105], v[154:157], v[194:197], v[102:105]
	v_mfma_f32_16x16x32_bf16 v[102:105], v[150:153], v[190:193], v[102:105]
	v_mfma_f32_16x16x32_bf16 v[106:109], v[150:153], v[198:201], v[106:109]
	v_mfma_f32_16x16x32_bf16 v[106:109], v[154:157], v[202:205], v[106:109]
	v_mfma_f32_16x16x32_bf16 v[110:113], v[154:157], v[210:213], v[110:113]
	v_mfma_f32_16x16x32_bf16 v[110:113], v[150:153], v[206:209], v[110:113]
	v_mfma_f32_16x16x32_bf16 v[46:49], v[158:161], v[206:209], v[46:49]
	v_mfma_f32_16x16x32_bf16 v[46:49], v[162:165], v[210:213], v[46:49]
	v_mfma_f32_16x16x32_bf16 v[42:45], v[162:165], v[202:205], v[42:45]
	v_mfma_f32_16x16x32_bf16 v[42:45], v[158:161], v[198:201], v[42:45]
	v_mfma_f32_16x16x32_bf16 v[38:41], v[158:161], v[190:193], v[38:41]
	v_mfma_f32_16x16x32_bf16 v[38:41], v[162:165], v[194:197], v[38:41]
	v_mfma_f32_16x16x32_bf16 v[26:29], v[162:165], v[186:189], v[26:29]
	v_mfma_f32_16x16x32_bf16 v[26:29], v[158:161], v[182:185], v[26:29]
	v_mfma_f32_16x16x32_bf16 v[114:117], v[166:169], v[182:185], v[114:117]
	v_mfma_f32_16x16x32_bf16 v[114:117], v[170:173], v[186:189], v[114:117]
	v_mfma_f32_16x16x32_bf16 v[118:121], v[170:173], v[194:197], v[118:121]
	v_mfma_f32_16x16x32_bf16 v[118:121], v[166:169], v[190:193], v[118:121]
	v_mfma_f32_16x16x32_bf16 v[122:125], v[166:169], v[198:201], v[122:125]
	v_mfma_f32_16x16x32_bf16 v[122:125], v[170:173], v[202:205], v[122:125]
	v_mfma_f32_16x16x32_bf16 v[126:129], v[170:173], v[210:213], v[126:129]
	v_mfma_f32_16x16x32_bf16 v[126:129], v[166:169], v[206:209], v[126:129]
	v_mfma_f32_16x16x32_bf16 v[62:65], v[174:177], v[206:209], v[62:65]
	v_mfma_f32_16x16x32_bf16 v[62:65], v[178:181], v[210:213], v[62:65]
	v_mfma_f32_16x16x32_bf16 v[58:61], v[178:181], v[202:205], v[58:61]
	v_mfma_f32_16x16x32_bf16 v[58:61], v[174:177], v[198:201], v[58:61]
	v_mfma_f32_16x16x32_bf16 v[54:57], v[174:177], v[190:193], v[54:57]
	v_mfma_f32_16x16x32_bf16 v[54:57], v[178:181], v[194:197], v[54:57]
	v_mfma_f32_16x16x32_bf16 v[50:53], v[178:181], v[186:189], v[50:53]
	v_mfma_f32_16x16x32_bf16 v[50:53], v[174:177], v[182:185], v[50:53]
	s_barrier
	s_nop 0
	s_add_i32 s78, 0, 0x18000
	s_add_i32 s79, 0, 0x1c000
	ds_read_b128 v[150:153], v248
	ds_read_b128 v[154:157], v248 offset:1024
	ds_read_b128 v[158:161], v248 offset:2048
	ds_read_b128 v[162:165], v248 offset:3072
	ds_read_b128 v[166:169], v249
	ds_read_b128 v[170:173], v249 offset:1024
	ds_read_b128 v[174:177], v249 offset:2048
	ds_read_b128 v[178:181], v249 offset:3072
	ds_read_b128 v[182:185], v149 offset:32768
	ds_read_b128 v[186:189], v149 offset:33792
	ds_read_b128 v[190:193], v149 offset:34816
	ds_read_b128 v[194:197], v149 offset:35840
	ds_read_b128 v[198:201], v149 offset:36864
	ds_read_b128 v[202:205], v149 offset:37888
	ds_read_b128 v[206:209], v149 offset:38912
	ds_read_b128 v[210:213], v149 offset:39936
	s_add_u32 s50, s54, 0x40000
	s_addc_u32 s51, s55, 0
	s_mov_b32 m0, s62
	s_nop 0
	global_load_lds_dwordx4 v226, s[50:51]
	s_mov_b32 m0, s63
	s_nop 0
	global_load_lds_dwordx4 v230, s[50:51]
	s_waitcnt vmcnt(8)
	s_waitcnt lgkmcnt(0)
	s_barrier
	v_mfma_f32_16x16x32_bf16 v[78:81], v[150:153], v[182:185], v[78:81]
	v_mfma_f32_16x16x32_bf16 v[78:81], v[154:157], v[186:189], v[78:81]
	v_mfma_f32_16x16x32_bf16 v[66:69], v[154:157], v[194:197], v[66:69]
	v_mfma_f32_16x16x32_bf16 v[66:69], v[150:153], v[190:193], v[66:69]
	v_mfma_f32_16x16x32_bf16 v[70:73], v[150:153], v[198:201], v[70:73]
	v_mfma_f32_16x16x32_bf16 v[70:73], v[154:157], v[202:205], v[70:73]
	v_mfma_f32_16x16x32_bf16 v[74:77], v[154:157], v[210:213], v[74:77]
	v_mfma_f32_16x16x32_bf16 v[74:77], v[150:153], v[206:209], v[74:77]
	v_mfma_f32_16x16x32_bf16 v[10:13], v[158:161], v[206:209], v[10:13]
	v_mfma_f32_16x16x32_bf16 v[10:13], v[162:165], v[210:213], v[10:13]
	v_mfma_f32_16x16x32_bf16 v[6:9], v[162:165], v[202:205], v[6:9]
	v_mfma_f32_16x16x32_bf16 v[6:9], v[158:161], v[198:201], v[6:9]
	v_mfma_f32_16x16x32_bf16 v[2:5], v[158:161], v[190:193], v[2:5]
	v_mfma_f32_16x16x32_bf16 v[2:5], v[162:165], v[194:197], v[2:5]
	v_mfma_f32_16x16x32_bf16 v[14:17], v[162:165], v[186:189], v[14:17]
	v_mfma_f32_16x16x32_bf16 v[14:17], v[158:161], v[182:185], v[14:17]
	v_mfma_f32_16x16x32_bf16 v[98:101], v[166:169], v[182:185], v[98:101]
	v_mfma_f32_16x16x32_bf16 v[98:101], v[170:173], v[186:189], v[98:101]
	v_mfma_f32_16x16x32_bf16 v[82:85], v[170:173], v[194:197], v[82:85]
	v_mfma_f32_16x16x32_bf16 v[82:85], v[166:169], v[190:193], v[82:85]
	v_mfma_f32_16x16x32_bf16 v[86:89], v[166:169], v[198:201], v[86:89]
	v_mfma_f32_16x16x32_bf16 v[86:89], v[170:173], v[202:205], v[86:89]
	v_mfma_f32_16x16x32_bf16 v[94:97], v[170:173], v[210:213], v[94:97]
	v_mfma_f32_16x16x32_bf16 v[94:97], v[166:169], v[206:209], v[94:97]
	v_mfma_f32_16x16x32_bf16 v[30:33], v[174:177], v[206:209], v[30:33]
	v_mfma_f32_16x16x32_bf16 v[30:33], v[178:181], v[210:213], v[30:33]
	v_mfma_f32_16x16x32_bf16 v[22:25], v[178:181], v[202:205], v[22:25]
	v_mfma_f32_16x16x32_bf16 v[22:25], v[174:177], v[198:201], v[22:25]
	v_mfma_f32_16x16x32_bf16 v[18:21], v[174:177], v[190:193], v[18:21]
	v_mfma_f32_16x16x32_bf16 v[18:21], v[178:181], v[194:197], v[18:21]
	v_mfma_f32_16x16x32_bf16 v[34:37], v[178:181], v[186:189], v[34:37]
	v_mfma_f32_16x16x32_bf16 v[34:37], v[174:177], v[182:185], v[34:37]
	s_barrier
	ds_read_b128 v[182:185], v149 offset:49152
	ds_read_b128 v[186:189], v149 offset:50176
	ds_read_b128 v[190:193], v149 offset:51200
	ds_read_b128 v[194:197], v149 offset:52224
	ds_read_b128 v[198:201], v149 offset:53248
	ds_read_b128 v[202:205], v149 offset:54272
	ds_read_b128 v[206:209], v149 offset:55296
	ds_read_b128 v[210:213], v149 offset:56320
	s_add_u32 s98, s52, 0x80
	s_addc_u32 s99, s53, 0
	s_add_u32 s100, s54, 0x80
	s_addc_u32 s101, s55, 0
	s_add_i32 s50, s78, s15
	s_mov_b32 m0, s50
	s_nop 0
	global_load_lds_dwordx4 v228, s[98:99]
	s_add_i32 m0, s50, 0x2000
	s_add_u32 s50, s52, 0x40080
	s_addc_u32 s51, s53, 0
	global_load_lds_dwordx4 v232, s[98:99]
	s_add_i32 s52, s79, s15
	s_mov_b32 m0, s52
	s_nop 0
	global_load_lds_dwordx4 v228, s[50:51]
	s_add_i32 m0, s52, 0x2000
	s_nop 0
	global_load_lds_dwordx4 v232, s[50:51]
	s_mov_b32 m0, s68
	s_nop 0
	global_load_lds_dwordx4 v226, s[100:101]
	s_mov_b32 m0, s69
	s_nop 0
	global_load_lds_dwordx4 v230, s[100:101]
	s_waitcnt vmcnt(8)
	s_waitcnt lgkmcnt(0)
	s_barrier
	v_mfma_f32_16x16x32_bf16 v[90:93], v[150:153], v[182:185], v[90:93]
	v_mfma_f32_16x16x32_bf16 v[90:93], v[154:157], v[186:189], v[90:93]
	v_mfma_f32_16x16x32_bf16 v[102:105], v[154:157], v[194:197], v[102:105]
	v_mfma_f32_16x16x32_bf16 v[102:105], v[150:153], v[190:193], v[102:105]
	v_mfma_f32_16x16x32_bf16 v[106:109], v[150:153], v[198:201], v[106:109]
	v_mfma_f32_16x16x32_bf16 v[106:109], v[154:157], v[202:205], v[106:109]
	v_mfma_f32_16x16x32_bf16 v[110:113], v[154:157], v[210:213], v[110:113]
	v_mfma_f32_16x16x32_bf16 v[110:113], v[150:153], v[206:209], v[110:113]
	v_mfma_f32_16x16x32_bf16 v[46:49], v[158:161], v[206:209], v[46:49]
	v_mfma_f32_16x16x32_bf16 v[46:49], v[162:165], v[210:213], v[46:49]
	v_mfma_f32_16x16x32_bf16 v[42:45], v[162:165], v[202:205], v[42:45]
	v_mfma_f32_16x16x32_bf16 v[42:45], v[158:161], v[198:201], v[42:45]
	v_mfma_f32_16x16x32_bf16 v[38:41], v[158:161], v[190:193], v[38:41]
	v_mfma_f32_16x16x32_bf16 v[38:41], v[162:165], v[194:197], v[38:41]
	v_mfma_f32_16x16x32_bf16 v[26:29], v[162:165], v[186:189], v[26:29]
	v_mfma_f32_16x16x32_bf16 v[26:29], v[158:161], v[182:185], v[26:29]
	v_mfma_f32_16x16x32_bf16 v[114:117], v[166:169], v[182:185], v[114:117]
	v_mfma_f32_16x16x32_bf16 v[114:117], v[170:173], v[186:189], v[114:117]
	v_mfma_f32_16x16x32_bf16 v[118:121], v[170:173], v[194:197], v[118:121]
	v_mfma_f32_16x16x32_bf16 v[118:121], v[166:169], v[190:193], v[118:121]
	v_mfma_f32_16x16x32_bf16 v[122:125], v[166:169], v[198:201], v[122:125]
	v_mfma_f32_16x16x32_bf16 v[122:125], v[170:173], v[202:205], v[122:125]
	v_mfma_f32_16x16x32_bf16 v[126:129], v[170:173], v[210:213], v[126:129]
	v_mfma_f32_16x16x32_bf16 v[126:129], v[166:169], v[206:209], v[126:129]
	v_mfma_f32_16x16x32_bf16 v[62:65], v[174:177], v[206:209], v[62:65]
	v_mfma_f32_16x16x32_bf16 v[62:65], v[178:181], v[210:213], v[62:65]
	v_mfma_f32_16x16x32_bf16 v[58:61], v[178:181], v[202:205], v[58:61]
	v_mfma_f32_16x16x32_bf16 v[58:61], v[174:177], v[198:201], v[58:61]
	v_mfma_f32_16x16x32_bf16 v[54:57], v[174:177], v[190:193], v[54:57]
	v_mfma_f32_16x16x32_bf16 v[54:57], v[178:181], v[194:197], v[54:57]
	v_mfma_f32_16x16x32_bf16 v[50:53], v[178:181], v[186:189], v[50:53]
	v_mfma_f32_16x16x32_bf16 v[50:53], v[174:177], v[182:185], v[50:53]
	s_barrier
	s_add_u32 s34, s34, 0x100
	s_addc_u32 s35, s35, 0
	s_add_u32 s21, s21, 0x100
	s_addc_u32 s23, s23, 0
	s_cmp_ge_i32 s77, s66
	s_mov_b32 s52, s77
	s_cbranch_scc0 .LBB0_872

.LBB0_1009:
	s_nop 0
	v_add_u32_e32 v0, s64, v187
	ds_read_b128 v[130:133], v0
	ds_read_b128 v[134:137], v0 offset:1024
	ds_read_b128 v[138:141], v0 offset:2048
	ds_read_b128 v[142:145], v0 offset:3072
	v_add_u32_e32 v0, s65, v187
	ds_read_b128 v[146:149], v0
	ds_read_b128 v[150:153], v0 offset:1024
	ds_read_b128 v[178:181], v0 offset:2048
	ds_read_b128 v[182:185], v0 offset:3072
	s_add_i32 s35, s42, 2
	s_add_u32 s43, s36, 0x3fc000
	s_addc_u32 s44, s37, 0
	s_cmp_eq_u32 s61, s42
	s_cselect_b32 s46, s28, s43
	s_cselect_b32 s47, s29, s44
	s_cselect_b32 s44, s30, s11
	s_cselect_b32 s45, s31, s27
	s_add_u32 s42, s46, 0x400000
	s_addc_u32 s43, s47, 0
	s_add_i32 m0, s51, 0xc000
	ds_read_b128 v[220:223], v215
	ds_read_b128 v[224:227], v215 offset:1024
	ds_read_b128 v[228:231], v215 offset:2048
	ds_read_b128 v[232:235], v215 offset:3072
	ds_read_b128 v[236:239], v215 offset:4096
	ds_read_b128 v[240:243], v215 offset:5120
	ds_read_b128 v[244:247], v215 offset:6144
	ds_read_b128 v[248:251], v215 offset:7168
	global_load_lds_dwordx4 v168, s[36:37]
	s_add_i32 m0, s51, 0xe000
	s_nop 0
	global_load_lds_dwordx4 v170, s[36:37]
	s_waitcnt vmcnt(8)
	s_waitcnt lgkmcnt(0)
	s_barrier
	v_mfma_f32_16x16x32_bf16 v[114:117], v[130:133], v[220:223], v[114:117]
	v_mfma_f32_16x16x32_bf16 v[114:117], v[134:137], v[224:227], v[114:117]
	v_mfma_f32_16x16x32_bf16 v[110:113], v[134:137], v[232:235], v[110:113]
	v_mfma_f32_16x16x32_bf16 v[110:113], v[130:133], v[228:231], v[110:113]
	v_mfma_f32_16x16x32_bf16 v[94:97], v[130:133], v[236:239], v[94:97]
	v_mfma_f32_16x16x32_bf16 v[94:97], v[134:137], v[240:243], v[94:97]
	v_mfma_f32_16x16x32_bf16 v[78:81], v[134:137], v[248:251], v[78:81]
	v_mfma_f32_16x16x32_bf16 v[78:81], v[130:133], v[244:247], v[78:81]
	v_mfma_f32_16x16x32_bf16 v[70:73], v[138:141], v[244:247], v[70:73]
	v_mfma_f32_16x16x32_bf16 v[70:73], v[142:145], v[248:251], v[70:73]
	v_mfma_f32_16x16x32_bf16 v[86:89], v[142:145], v[240:243], v[86:89]
	v_mfma_f32_16x16x32_bf16 v[86:89], v[138:141], v[236:239], v[86:89]
	v_mfma_f32_16x16x32_bf16 v[102:105], v[138:141], v[228:231], v[102:105]
	v_mfma_f32_16x16x32_bf16 v[102:105], v[142:145], v[232:235], v[102:105]
	v_mfma_f32_16x16x32_bf16 v[118:121], v[142:145], v[224:227], v[118:121]
	v_mfma_f32_16x16x32_bf16 v[118:121], v[138:141], v[220:223], v[118:121]
	v_mfma_f32_16x16x32_bf16 v[126:129], v[146:149], v[220:223], v[126:129]
	v_mfma_f32_16x16x32_bf16 v[126:129], v[150:153], v[224:227], v[126:129]
	v_mfma_f32_16x16x32_bf16 v[106:109], v[150:153], v[232:235], v[106:109]
	v_mfma_f32_16x16x32_bf16 v[106:109], v[146:149], v[228:231], v[106:109]
	v_mfma_f32_16x16x32_bf16 v[90:93], v[146:149], v[236:239], v[90:93]
	v_mfma_f32_16x16x32_bf16 v[90:93], v[150:153], v[240:243], v[90:93]
	v_mfma_f32_16x16x32_bf16 v[74:77], v[150:153], v[248:251], v[74:77]
	v_mfma_f32_16x16x32_bf16 v[74:77], v[146:149], v[244:247], v[74:77]
	v_mfma_f32_16x16x32_bf16 v[66:69], v[178:181], v[244:247], v[66:69]
	v_mfma_f32_16x16x32_bf16 v[66:69], v[182:185], v[248:251], v[66:69]
	v_mfma_f32_16x16x32_bf16 v[82:85], v[182:185], v[240:243], v[82:85]
	v_mfma_f32_16x16x32_bf16 v[82:85], v[178:181], v[236:239], v[82:85]
	v_mfma_f32_16x16x32_bf16 v[98:101], v[178:181], v[228:231], v[98:101]
	v_mfma_f32_16x16x32_bf16 v[98:101], v[182:185], v[232:235], v[98:101]
	v_mfma_f32_16x16x32_bf16 v[122:125], v[182:185], v[224:227], v[122:125]
	v_mfma_f32_16x16x32_bf16 v[122:125], v[178:181], v[220:223], v[122:125]
	s_barrier
	s_nop 0
	s_add_i32 s69, s64, s49
	s_mov_b32 m0, s69
	ds_read_b128 v[220:223], v215 offset:16384
	ds_read_b128 v[224:227], v215 offset:17408
	ds_read_b128 v[228:231], v215 offset:18432
	ds_read_b128 v[232:235], v215 offset:19456
	ds_read_b128 v[236:239], v215 offset:20480
	ds_read_b128 v[240:243], v215 offset:21504
	ds_read_b128 v[244:247], v215 offset:22528
	ds_read_b128 v[248:251], v215 offset:23552
	global_load_lds_dwordx4 v156, s[44:45]
	s_add_i32 m0, s69, 0x2000
	s_add_u32 s70, s44, 0xb0000
	v_lshl_add_u64 v[172:173], s[44:45], 0, v[160:161]
	s_addc_u32 s71, s45, 0
	s_add_i32 s69, s65, s49
	global_load_lds_dwordx4 v160, s[44:45]
	s_mov_b32 m0, s69
	s_nop 0
	global_load_lds_dwordx4 v156, s[70:71]
	s_add_i32 m0, s69, 0x2000
	s_nop 0
	global_load_lds_dwordx4 v160, s[70:71]
	s_mov_b32 m0, s51
	s_nop 0
	global_load_lds_dwordx4 v154, s[46:47]
	s_mov_b32 m0, s52
	s_nop 0
	global_load_lds_dwordx4 v158, s[46:47]
	s_waitcnt vmcnt(8)
	s_waitcnt lgkmcnt(0)
	s_barrier
	v_mfma_f32_16x16x32_bf16 v[50:53], v[130:133], v[220:223], v[50:53]
	v_mfma_f32_16x16x32_bf16 v[50:53], v[134:137], v[224:227], v[50:53]
	v_mfma_f32_16x16x32_bf16 v[54:57], v[142:145], v[224:227], v[54:57]
	v_mfma_f32_16x16x32_bf16 v[54:57], v[138:141], v[220:223], v[54:57]
	v_mfma_f32_16x16x32_bf16 v[46:49], v[130:133], v[228:231], v[46:49]
	v_mfma_f32_16x16x32_bf16 v[46:49], v[134:137], v[232:235], v[46:49]
	v_mfma_f32_16x16x32_bf16 v[38:41], v[142:145], v[232:235], v[38:41]
	v_mfma_f32_16x16x32_bf16 v[38:41], v[138:141], v[228:231], v[38:41]
	v_mfma_f32_16x16x32_bf16 v[30:33], v[130:133], v[236:239], v[30:33]
	v_mfma_f32_16x16x32_bf16 v[30:33], v[134:137], v[240:243], v[30:33]
	v_mfma_f32_16x16x32_bf16 v[22:25], v[142:145], v[240:243], v[22:25]
	v_mfma_f32_16x16x32_bf16 v[22:25], v[138:141], v[236:239], v[22:25]
	v_mfma_f32_16x16x32_bf16 v[14:17], v[130:133], v[244:247], v[14:17]
	v_mfma_f32_16x16x32_bf16 v[14:17], v[134:137], v[248:251], v[14:17]
	v_mfma_f32_16x16x32_bf16 v[62:65], v[150:153], v[224:227], v[62:65]
	v_mfma_f32_16x16x32_bf16 v[62:65], v[146:149], v[220:223], v[62:65]
	v_mfma_f32_16x16x32_bf16 v[58:61], v[178:181], v[220:223], v[58:61]
	v_mfma_f32_16x16x32_bf16 v[58:61], v[182:185], v[224:227], v[58:61]
	v_mfma_f32_16x16x32_bf16 v[42:45], v[150:153], v[232:235], v[42:45]
	v_mfma_f32_16x16x32_bf16 v[42:45], v[146:149], v[228:231], v[42:45]
	v_mfma_f32_16x16x32_bf16 v[34:37], v[178:181], v[228:231], v[34:37]
	v_mfma_f32_16x16x32_bf16 v[34:37], v[182:185], v[232:235], v[34:37]
	v_mfma_f32_16x16x32_bf16 v[26:29], v[150:153], v[240:243], v[26:29]
	v_mfma_f32_16x16x32_bf16 v[26:29], v[146:149], v[236:239], v[26:29]
	v_mfma_f32_16x16x32_bf16 v[18:21], v[178:181], v[236:239], v[18:21]
	v_mfma_f32_16x16x32_bf16 v[18:21], v[182:185], v[240:243], v[18:21]
	v_mfma_f32_16x16x32_bf16 v[10:13], v[150:153], v[248:251], v[10:13]
	v_mfma_f32_16x16x32_bf16 v[10:13], v[146:149], v[244:247], v[10:13]
	v_mfma_f32_16x16x32_bf16 v[6:9], v[138:141], v[244:247], v[6:9]
	v_mfma_f32_16x16x32_bf16 v[6:9], v[142:145], v[248:251], v[6:9]
	v_mfma_f32_16x16x32_bf16 v[0:3], v[178:181], v[244:247], v[2:5]
	v_mfma_f32_16x16x32_bf16 v[0:3], v[182:185], v[248:251], v[0:3]
	s_barrier
	s_add_i32 s69, 0, 0x18000
	v_add_u32_e32 v4, s69, v187
	s_add_i32 s70, 0, 0x1c000
	ds_read_b128 v[130:133], v4
	ds_read_b128 v[134:137], v4 offset:1024
	ds_read_b128 v[138:141], v4 offset:2048
	ds_read_b128 v[142:145], v4 offset:3072
	v_add_u32_e32 v4, s70, v187
	ds_read_b128 v[146:149], v4
	ds_read_b128 v[150:153], v4 offset:1024
	ds_read_b128 v[178:181], v4 offset:2048
	ds_read_b128 v[182:185], v4 offset:3072
	s_add_u32 s46, s46, 0x4000
	s_addc_u32 s47, s47, 0
	s_mov_b32 m0, s53
	ds_read_b128 v[220:223], v215 offset:32768
	ds_read_b128 v[224:227], v215 offset:33792
	ds_read_b128 v[228:231], v215 offset:34816
	ds_read_b128 v[232:235], v215 offset:35840
	ds_read_b128 v[236:239], v215 offset:36864
	ds_read_b128 v[240:243], v215 offset:37888
	ds_read_b128 v[244:247], v215 offset:38912
	ds_read_b128 v[248:251], v215 offset:39936
	global_load_lds_dwordx4 v154, s[46:47]
	s_mov_b32 m0, s54
	s_nop 0
	global_load_lds_dwordx4 v158, s[46:47]
	s_waitcnt vmcnt(8)
	s_waitcnt lgkmcnt(0)
	s_barrier
	v_mfma_f32_16x16x32_bf16 v[114:117], v[130:133], v[220:223], v[114:117]
	v_mfma_f32_16x16x32_bf16 v[114:117], v[134:137], v[224:227], v[114:117]
	v_mfma_f32_16x16x32_bf16 v[110:113], v[134:137], v[232:235], v[110:113]
	v_mfma_f32_16x16x32_bf16 v[110:113], v[130:133], v[228:231], v[110:113]
	v_mfma_f32_16x16x32_bf16 v[94:97], v[130:133], v[236:239], v[94:97]
	v_mfma_f32_16x16x32_bf16 v[94:97], v[134:137], v[240:243], v[94:97]
	v_mfma_f32_16x16x32_bf16 v[78:81], v[134:137], v[248:251], v[78:81]
	v_mfma_f32_16x16x32_bf16 v[78:81], v[130:133], v[244:247], v[78:81]
	v_mfma_f32_16x16x32_bf16 v[70:73], v[138:141], v[244:247], v[70:73]
	v_mfma_f32_16x16x32_bf16 v[70:73], v[142:145], v[248:251], v[70:73]
	v_mfma_f32_16x16x32_bf16 v[86:89], v[142:145], v[240:243], v[86:89]
	v_mfma_f32_16x16x32_bf16 v[86:89], v[138:141], v[236:239], v[86:89]
	v_mfma_f32_16x16x32_bf16 v[102:105], v[138:141], v[228:231], v[102:105]
	v_mfma_f32_16x16x32_bf16 v[102:105], v[142:145], v[232:235], v[102:105]
	v_mfma_f32_16x16x32_bf16 v[118:121], v[142:145], v[224:227], v[118:121]
	v_mfma_f32_16x16x32_bf16 v[118:121], v[138:141], v[220:223], v[118:121]
	v_mfma_f32_16x16x32_bf16 v[126:129], v[146:149], v[220:223], v[126:129]
	v_mfma_f32_16x16x32_bf16 v[126:129], v[150:153], v[224:227], v[126:129]
	v_mfma_f32_16x16x32_bf16 v[106:109], v[150:153], v[232:235], v[106:109]
	v_mfma_f32_16x16x32_bf16 v[106:109], v[146:149], v[228:231], v[106:109]
	v_mfma_f32_16x16x32_bf16 v[90:93], v[146:149], v[236:239], v[90:93]
	v_mfma_f32_16x16x32_bf16 v[90:93], v[150:153], v[240:243], v[90:93]
	v_mfma_f32_16x16x32_bf16 v[74:77], v[150:153], v[248:251], v[74:77]
	v_mfma_f32_16x16x32_bf16 v[74:77], v[146:149], v[244:247], v[74:77]
	v_mfma_f32_16x16x32_bf16 v[66:69], v[178:181], v[244:247], v[66:69]
	v_mfma_f32_16x16x32_bf16 v[66:69], v[182:185], v[248:251], v[66:69]
	v_mfma_f32_16x16x32_bf16 v[82:85], v[182:185], v[240:243], v[82:85]
	v_mfma_f32_16x16x32_bf16 v[82:85], v[178:181], v[236:239], v[82:85]
	v_mfma_f32_16x16x32_bf16 v[98:101], v[178:181], v[228:231], v[98:101]
	v_mfma_f32_16x16x32_bf16 v[98:101], v[182:185], v[232:235], v[98:101]
	v_mfma_f32_16x16x32_bf16 v[122:125], v[182:185], v[224:227], v[122:125]
	v_mfma_f32_16x16x32_bf16 v[122:125], v[178:181], v[220:223], v[122:125]
	s_barrier
	s_nop 0
	s_add_i32 s46, s69, s49
	s_mov_b32 m0, s46
	ds_read_b128 v[220:223], v215 offset:49152
	ds_read_b128 v[224:227], v215 offset:50176
	ds_read_b128 v[228:231], v215 offset:51200
	ds_read_b128 v[232:235], v215 offset:52224
	ds_read_b128 v[236:239], v215 offset:53248
	ds_read_b128 v[240:243], v215 offset:54272
	ds_read_b128 v[244:247], v215 offset:55296
	ds_read_b128 v[248:251], v215 offset:56320
	s_add_u32 s98, s44, s18
	s_addc_u32 s99, s45, s19
	global_load_lds_dwordx4 v156, s[98:99]
	s_add_i32 m0, s46, 0x2000
	s_add_u32 s44, s44, 0xb0080
	v_lshl_add_u64 v[4:5], v[172:173], 0, s[18:19]
	s_addc_u32 s45, s45, 0
	s_add_i32 s46, s70, s49
	global_load_lds_dwordx4 v[4:5], off
	s_mov_b32 m0, s46
	s_nop 0
	global_load_lds_dwordx4 v156, s[44:45]
	s_add_i32 m0, s46, 0x2000
	s_nop 0
	global_load_lds_dwordx4 v160, s[44:45]
	s_mov_b32 m0, s59
	s_nop 0
	global_load_lds_dwordx4 v154, s[42:43]
	s_mov_b32 m0, s60
	s_nop 0
	global_load_lds_dwordx4 v158, s[42:43]
	s_waitcnt vmcnt(8)
	s_waitcnt lgkmcnt(0)
	s_barrier
	v_mfma_f32_16x16x32_bf16 v[50:53], v[130:133], v[220:223], v[50:53]
	v_mfma_f32_16x16x32_bf16 v[50:53], v[134:137], v[224:227], v[50:53]
	v_mfma_f32_16x16x32_bf16 v[54:57], v[142:145], v[224:227], v[54:57]
	v_mfma_f32_16x16x32_bf16 v[54:57], v[138:141], v[220:223], v[54:57]
	v_mfma_f32_16x16x32_bf16 v[46:49], v[130:133], v[228:231], v[46:49]
	v_mfma_f32_16x16x32_bf16 v[46:49], v[134:137], v[232:235], v[46:49]
	v_mfma_f32_16x16x32_bf16 v[38:41], v[142:145], v[232:235], v[38:41]
	v_mfma_f32_16x16x32_bf16 v[38:41], v[138:141], v[228:231], v[38:41]
	v_mfma_f32_16x16x32_bf16 v[30:33], v[130:133], v[236:239], v[30:33]
	v_mfma_f32_16x16x32_bf16 v[30:33], v[134:137], v[240:243], v[30:33]
	v_mfma_f32_16x16x32_bf16 v[22:25], v[142:145], v[240:243], v[22:25]
	v_mfma_f32_16x16x32_bf16 v[22:25], v[138:141], v[236:239], v[22:25]
	v_mfma_f32_16x16x32_bf16 v[14:17], v[130:133], v[244:247], v[14:17]
	v_mfma_f32_16x16x32_bf16 v[14:17], v[134:137], v[248:251], v[14:17]
	v_mfma_f32_16x16x32_bf16 v[62:65], v[150:153], v[224:227], v[62:65]
	v_mfma_f32_16x16x32_bf16 v[62:65], v[146:149], v[220:223], v[62:65]
	v_mfma_f32_16x16x32_bf16 v[58:61], v[178:181], v[220:223], v[58:61]
	v_mfma_f32_16x16x32_bf16 v[58:61], v[182:185], v[224:227], v[58:61]
	v_mfma_f32_16x16x32_bf16 v[42:45], v[150:153], v[232:235], v[42:45]
	v_mfma_f32_16x16x32_bf16 v[42:45], v[146:149], v[228:231], v[42:45]
	v_mfma_f32_16x16x32_bf16 v[34:37], v[178:181], v[228:231], v[34:37]
	v_mfma_f32_16x16x32_bf16 v[34:37], v[182:185], v[232:235], v[34:37]
	v_mfma_f32_16x16x32_bf16 v[26:29], v[150:153], v[240:243], v[26:29]
	v_mfma_f32_16x16x32_bf16 v[26:29], v[146:149], v[236:239], v[26:29]
	v_mfma_f32_16x16x32_bf16 v[18:21], v[178:181], v[236:239], v[18:21]
	v_mfma_f32_16x16x32_bf16 v[18:21], v[182:185], v[240:243], v[18:21]
	v_mfma_f32_16x16x32_bf16 v[10:13], v[150:153], v[248:251], v[10:13]
	v_mfma_f32_16x16x32_bf16 v[10:13], v[146:149], v[244:247], v[10:13]
	v_mfma_f32_16x16x32_bf16 v[4:7], v[138:141], v[244:247], v[6:9]
	v_mfma_f32_16x16x32_bf16 v[6:9], v[142:145], v[248:251], v[4:7]
	v_mfma_f32_16x16x32_bf16 v[0:3], v[178:181], v[244:247], v[0:3]
	v_mfma_f32_16x16x32_bf16 v[2:5], v[182:185], v[248:251], v[0:3]
	s_barrier
	s_add_u32 s11, s11, 0x100
	s_addc_u32 s27, s27, 0
	s_add_u32 s36, s36, 0x800000
	s_addc_u32 s37, s37, 0
	s_cmp_ge_i32 s35, s58
	s_mov_b32 s42, s35
	s_cbranch_scc0 .LBB0_1009
	v_mov_b64_e32 v[234:235], v[174:175]
	s_and_b64 vcc, exec, s[22:23]
	s_cbranch_vccnz .LBB0_980
	s_branch .LBB0_981
